# misc routine with a grid-size independent unit loop (h = wave*G + c, step 8*G); otherwise as the register-only version
# baseline (speedup 1.0000x reference)
.LBB0_359:
	s_mov_b64 exec, -1
	v_readfirstlane_b32 s4, v190
	s_lshr_b32 s4, s4, 6
	v_readlane_b32 s5, v253, 14
	s_mul_i32 s6, s4, s33
	s_add_i32 s5, s6, s5
	s_lshl_b32 s48, s33, 3
	s_load_dwordx2 s[2:3], s[0:1], 0x100
	v_and_b32_e32 v0, 63, v190
	v_and_b32_e32 v1, 15, v0
	v_lshrrev_b32_e32 v3, 4, v0
	v_lshlrev_b32_e32 v3, 4, v3
	v_mul_u32_u24_e32 v2, 0x140, v1
	v_add_u32_e32 v2, v2, v3
	v_lshl_add_u32 v1, v1, 12, v3
	s_waitcnt lgkmcnt(0)
.Lmisc_unit:
	s_cmpk_gt_u32 s5, 0x21f
	s_cbranch_scc1 .Lmisc_done
	s_lshl_b32 s6, s5, 17
	s_lshr_b32 s7, s5, 15
	s_add_u32 s8, s2, s6
	s_addc_u32 s9, s3, s7
	s_add_u32 s8, s8, 0xe144d00
	s_addc_u32 s9, s9, 0
	s_add_u32 s16, s8, 0x10000
	s_addc_u32 s17, s9, 0
	s_add_u32 s18, s2, 0x1000000
	s_addc_u32 s19, s3, 0
	s_add_u32 s28, s2, 0x1010000
	s_addc_u32 s29, s3, 0
	s_add_u32 s30, s2, 0x1020000
	s_addc_u32 s31, s3, 0
	s_add_u32 s34, s2, 0x1030000
	s_addc_u32 s35, s3, 0
	s_add_u32 s36, s2, 0x1040000
	s_addc_u32 s37, s3, 0
	s_add_u32 s38, s2, 0x8884000
	s_addc_u32 s39, s3, 0
	s_mul_i32 s6, s5, 0x2800
	s_mul_hi_u32 s7, s5, 0x2800
	s_add_u32 s40, s2, s6
	s_addc_u32 s41, s3, s7
	s_add_u32 s40, s40, 0x21344d00
	s_addc_u32 s41, s41, 0
	s_add_u32 s46, s40, 0x1400
	s_addc_u32 s47, s41, 0
	v_mov_b64_e32 v[32:33], 0
	v_mov_b64_e32 v[34:35], 0
	v_mov_b64_e32 v[36:37], 0
	v_mov_b64_e32 v[38:39], 0
	v_mov_b64_e32 v[40:41], 0
	v_mov_b64_e32 v[42:43], 0
	v_mov_b64_e32 v[44:45], 0
	v_mov_b64_e32 v[46:47], 0
	v_mov_b64_e32 v[48:49], 0
	v_mov_b64_e32 v[50:51], 0
	v_mov_b64_e32 v[52:53], 0
	v_mov_b64_e32 v[54:55], 0
	v_mov_b64_e32 v[56:57], 0
	v_mov_b64_e32 v[58:59], 0
	v_mov_b64_e32 v[60:61], 0
	v_mov_b64_e32 v[62:63], 0
	v_mov_b64_e32 v[64:65], 0
	v_mov_b64_e32 v[66:67], 0
	v_mov_b64_e32 v[68:69], 0
	v_mov_b64_e32 v[70:71], 0
	global_load_dwordx4 v[72:75], v1, s[8:9]
	global_load_dwordx4 v[76:79], v1, s[16:17]
	global_load_dwordx4 v[80:83], v1, s[18:19]
	global_load_dwordx4 v[84:87], v1, s[28:29]
	global_load_dwordx4 v[88:91], v1, s[30:31]
	global_load_dwordx4 v[92:95], v1, s[34:35]
	global_load_dwordx4 v[96:99], v1, s[36:37]
	global_load_dwordx4 v[100:103], v1, s[8:9] offset:64
	global_load_dwordx4 v[104:107], v1, s[16:17] offset:64
	global_load_dwordx4 v[108:111], v1, s[18:19] offset:64
	global_load_dwordx4 v[112:115], v1, s[28:29] offset:64
	global_load_dwordx4 v[116:119], v1, s[30:31] offset:64
	global_load_dwordx4 v[120:123], v1, s[34:35] offset:64
	global_load_dwordx4 v[124:127], v1, s[36:37] offset:64
	global_load_dwordx4 v[128:131], v1, s[8:9] offset:128
	global_load_dwordx4 v[132:135], v1, s[16:17] offset:128
	global_load_dwordx4 v[136:139], v1, s[18:19] offset:128
	global_load_dwordx4 v[140:143], v1, s[28:29] offset:128
	global_load_dwordx4 v[144:147], v1, s[30:31] offset:128
	global_load_dwordx4 v[148:151], v1, s[34:35] offset:128
	global_load_dwordx4 v[152:155], v1, s[36:37] offset:128
	global_load_dwordx4 v[156:159], v1, s[8:9] offset:192
	global_load_dwordx4 v[172:175], v1, s[16:17] offset:192
	global_load_dwordx4 v[176:179], v1, s[18:19] offset:192
	global_load_dwordx4 v[180:183], v1, s[28:29] offset:192
	global_load_dwordx4 v[184:187], v1, s[30:31] offset:192
	global_load_dwordx4 v[196:199], v1, s[34:35] offset:192
	global_load_dwordx4 v[200:203], v1, s[36:37] offset:192
	global_load_dwordx4 v[204:207], v1, s[8:9] offset:256
	global_load_dwordx4 v[208:211], v1, s[16:17] offset:256
	global_load_dwordx4 v[212:215], v1, s[18:19] offset:256
	global_load_dwordx4 v[234:237], v1, s[28:29] offset:256
	global_load_dwordx4 v[238:241], v1, s[30:31] offset:256
	global_load_dwordx4 v[242:245], v1, s[34:35] offset:256
	global_load_dwordx4 v[246:249], v1, s[36:37] offset:256
	s_waitcnt vmcnt(28)
	v_mfma_f32_16x16x32_bf16 v[32:35], v[80:83], v[72:75], v[32:35]
	v_mfma_f32_16x16x32_bf16 v[52:55], v[80:83], v[76:79], v[52:55]
	v_mfma_f32_16x16x32_bf16 v[36:39], v[84:87], v[72:75], v[36:39]
	v_mfma_f32_16x16x32_bf16 v[56:59], v[84:87], v[76:79], v[56:59]
	v_mfma_f32_16x16x32_bf16 v[40:43], v[88:91], v[72:75], v[40:43]
	v_mfma_f32_16x16x32_bf16 v[60:63], v[88:91], v[76:79], v[60:63]
	v_mfma_f32_16x16x32_bf16 v[44:47], v[92:95], v[72:75], v[44:47]
	v_mfma_f32_16x16x32_bf16 v[64:67], v[92:95], v[76:79], v[64:67]
	v_mfma_f32_16x16x32_bf16 v[48:51], v[96:99], v[72:75], v[48:51]
	v_mfma_f32_16x16x32_bf16 v[68:71], v[96:99], v[76:79], v[68:71]
	global_load_dwordx4 v[72:75], v1, s[8:9] offset:320
	global_load_dwordx4 v[76:79], v1, s[16:17] offset:320
	global_load_dwordx4 v[80:83], v1, s[18:19] offset:320
	global_load_dwordx4 v[84:87], v1, s[28:29] offset:320
	global_load_dwordx4 v[88:91], v1, s[30:31] offset:320
	global_load_dwordx4 v[92:95], v1, s[34:35] offset:320
	global_load_dwordx4 v[96:99], v1, s[36:37] offset:320
	s_waitcnt vmcnt(28)
	v_mfma_f32_16x16x32_bf16 v[32:35], v[108:111], v[100:103], v[32:35]
	v_mfma_f32_16x16x32_bf16 v[52:55], v[108:111], v[104:107], v[52:55]
	v_mfma_f32_16x16x32_bf16 v[36:39], v[112:115], v[100:103], v[36:39]
	v_mfma_f32_16x16x32_bf16 v[56:59], v[112:115], v[104:107], v[56:59]
	v_mfma_f32_16x16x32_bf16 v[40:43], v[116:119], v[100:103], v[40:43]
	v_mfma_f32_16x16x32_bf16 v[60:63], v[116:119], v[104:107], v[60:63]
	v_mfma_f32_16x16x32_bf16 v[44:47], v[120:123], v[100:103], v[44:47]
	v_mfma_f32_16x16x32_bf16 v[64:67], v[120:123], v[104:107], v[64:67]
	v_mfma_f32_16x16x32_bf16 v[48:51], v[124:127], v[100:103], v[48:51]
	v_mfma_f32_16x16x32_bf16 v[68:71], v[124:127], v[104:107], v[68:71]
	global_load_dwordx4 v[100:103], v1, s[8:9] offset:384
	global_load_dwordx4 v[104:107], v1, s[16:17] offset:384
	global_load_dwordx4 v[108:111], v1, s[18:19] offset:384
	global_load_dwordx4 v[112:115], v1, s[28:29] offset:384
	global_load_dwordx4 v[116:119], v1, s[30:31] offset:384
	global_load_dwordx4 v[120:123], v1, s[34:35] offset:384
	global_load_dwordx4 v[124:127], v1, s[36:37] offset:384
	s_waitcnt vmcnt(28)
	v_mfma_f32_16x16x32_bf16 v[32:35], v[136:139], v[128:131], v[32:35]
	v_mfma_f32_16x16x32_bf16 v[52:55], v[136:139], v[132:135], v[52:55]
	v_mfma_f32_16x16x32_bf16 v[36:39], v[140:143], v[128:131], v[36:39]
	v_mfma_f32_16x16x32_bf16 v[56:59], v[140:143], v[132:135], v[56:59]
	v_mfma_f32_16x16x32_bf16 v[40:43], v[144:147], v[128:131], v[40:43]
	v_mfma_f32_16x16x32_bf16 v[60:63], v[144:147], v[132:135], v[60:63]
	v_mfma_f32_16x16x32_bf16 v[44:47], v[148:151], v[128:131], v[44:47]
	v_mfma_f32_16x16x32_bf16 v[64:67], v[148:151], v[132:135], v[64:67]
	v_mfma_f32_16x16x32_bf16 v[48:51], v[152:155], v[128:131], v[48:51]
	v_mfma_f32_16x16x32_bf16 v[68:71], v[152:155], v[132:135], v[68:71]
	global_load_dwordx4 v[128:131], v1, s[8:9] offset:448
	global_load_dwordx4 v[132:135], v1, s[16:17] offset:448
	global_load_dwordx4 v[136:139], v1, s[18:19] offset:448
	global_load_dwordx4 v[140:143], v1, s[28:29] offset:448
	global_load_dwordx4 v[144:147], v1, s[30:31] offset:448
	global_load_dwordx4 v[148:151], v1, s[34:35] offset:448
	global_load_dwordx4 v[152:155], v1, s[36:37] offset:448
	s_waitcnt vmcnt(28)
	v_mfma_f32_16x16x32_bf16 v[32:35], v[176:179], v[156:159], v[32:35]
	v_mfma_f32_16x16x32_bf16 v[52:55], v[176:179], v[172:175], v[52:55]
	v_mfma_f32_16x16x32_bf16 v[36:39], v[180:183], v[156:159], v[36:39]
	v_mfma_f32_16x16x32_bf16 v[56:59], v[180:183], v[172:175], v[56:59]
	v_mfma_f32_16x16x32_bf16 v[40:43], v[184:187], v[156:159], v[40:43]
	v_mfma_f32_16x16x32_bf16 v[60:63], v[184:187], v[172:175], v[60:63]
	v_mfma_f32_16x16x32_bf16 v[44:47], v[196:199], v[156:159], v[44:47]
	v_mfma_f32_16x16x32_bf16 v[64:67], v[196:199], v[172:175], v[64:67]
	v_mfma_f32_16x16x32_bf16 v[48:51], v[200:203], v[156:159], v[48:51]
	v_mfma_f32_16x16x32_bf16 v[68:71], v[200:203], v[172:175], v[68:71]
	global_load_dwordx4 v[156:159], v1, s[8:9] offset:512
	global_load_dwordx4 v[172:175], v1, s[16:17] offset:512
	global_load_dwordx4 v[176:179], v1, s[18:19] offset:512
	global_load_dwordx4 v[180:183], v1, s[28:29] offset:512
	global_load_dwordx4 v[184:187], v1, s[30:31] offset:512
	global_load_dwordx4 v[196:199], v1, s[34:35] offset:512
	global_load_dwordx4 v[200:203], v1, s[36:37] offset:512
	s_waitcnt vmcnt(28)
	v_mfma_f32_16x16x32_bf16 v[32:35], v[212:215], v[204:207], v[32:35]
	v_mfma_f32_16x16x32_bf16 v[52:55], v[212:215], v[208:211], v[52:55]
	v_mfma_f32_16x16x32_bf16 v[36:39], v[234:237], v[204:207], v[36:39]
	v_mfma_f32_16x16x32_bf16 v[56:59], v[234:237], v[208:211], v[56:59]
	v_mfma_f32_16x16x32_bf16 v[40:43], v[238:241], v[204:207], v[40:43]
	v_mfma_f32_16x16x32_bf16 v[60:63], v[238:241], v[208:211], v[60:63]
	v_mfma_f32_16x16x32_bf16 v[44:47], v[242:245], v[204:207], v[44:47]
	v_mfma_f32_16x16x32_bf16 v[64:67], v[242:245], v[208:211], v[64:67]
	v_mfma_f32_16x16x32_bf16 v[48:51], v[246:249], v[204:207], v[48:51]
	v_mfma_f32_16x16x32_bf16 v[68:71], v[246:249], v[208:211], v[68:71]
	global_load_dwordx4 v[204:207], v1, s[8:9] offset:576
	global_load_dwordx4 v[208:211], v1, s[16:17] offset:576
	global_load_dwordx4 v[212:215], v1, s[18:19] offset:576
	global_load_dwordx4 v[234:237], v1, s[28:29] offset:576
	global_load_dwordx4 v[238:241], v1, s[30:31] offset:576
	global_load_dwordx4 v[242:245], v1, s[34:35] offset:576
	global_load_dwordx4 v[246:249], v1, s[36:37] offset:576
	s_waitcnt vmcnt(28)
	v_mfma_f32_16x16x32_bf16 v[32:35], v[80:83], v[72:75], v[32:35]
	v_mfma_f32_16x16x32_bf16 v[52:55], v[80:83], v[76:79], v[52:55]
	v_mfma_f32_16x16x32_bf16 v[36:39], v[84:87], v[72:75], v[36:39]
	v_mfma_f32_16x16x32_bf16 v[56:59], v[84:87], v[76:79], v[56:59]
	v_mfma_f32_16x16x32_bf16 v[40:43], v[88:91], v[72:75], v[40:43]
	v_mfma_f32_16x16x32_bf16 v[60:63], v[88:91], v[76:79], v[60:63]
	v_mfma_f32_16x16x32_bf16 v[44:47], v[92:95], v[72:75], v[44:47]
	v_mfma_f32_16x16x32_bf16 v[64:67], v[92:95], v[76:79], v[64:67]
	v_mfma_f32_16x16x32_bf16 v[48:51], v[96:99], v[72:75], v[48:51]
	v_mfma_f32_16x16x32_bf16 v[68:71], v[96:99], v[76:79], v[68:71]
	global_load_dwordx4 v[72:75], v1, s[8:9] offset:640
	global_load_dwordx4 v[76:79], v1, s[16:17] offset:640
	global_load_dwordx4 v[80:83], v1, s[18:19] offset:640
	global_load_dwordx4 v[84:87], v1, s[28:29] offset:640
	global_load_dwordx4 v[88:91], v1, s[30:31] offset:640
	global_load_dwordx4 v[92:95], v1, s[34:35] offset:640
	global_load_dwordx4 v[96:99], v1, s[36:37] offset:640
	s_waitcnt vmcnt(28)
	v_mfma_f32_16x16x32_bf16 v[32:35], v[108:111], v[100:103], v[32:35]
	v_mfma_f32_16x16x32_bf16 v[52:55], v[108:111], v[104:107], v[52:55]
	v_mfma_f32_16x16x32_bf16 v[36:39], v[112:115], v[100:103], v[36:39]
	v_mfma_f32_16x16x32_bf16 v[56:59], v[112:115], v[104:107], v[56:59]
	v_mfma_f32_16x16x32_bf16 v[40:43], v[116:119], v[100:103], v[40:43]
	v_mfma_f32_16x16x32_bf16 v[60:63], v[116:119], v[104:107], v[60:63]
	v_mfma_f32_16x16x32_bf16 v[44:47], v[120:123], v[100:103], v[44:47]
	v_mfma_f32_16x16x32_bf16 v[64:67], v[120:123], v[104:107], v[64:67]
	v_mfma_f32_16x16x32_bf16 v[48:51], v[124:127], v[100:103], v[48:51]
	v_mfma_f32_16x16x32_bf16 v[68:71], v[124:127], v[104:107], v[68:71]
	global_load_dwordx4 v[100:103], v1, s[8:9] offset:704
	global_load_dwordx4 v[104:107], v1, s[16:17] offset:704
	global_load_dwordx4 v[108:111], v1, s[18:19] offset:704
	global_load_dwordx4 v[112:115], v1, s[28:29] offset:704
	global_load_dwordx4 v[116:119], v1, s[30:31] offset:704
	global_load_dwordx4 v[120:123], v1, s[34:35] offset:704
	global_load_dwordx4 v[124:127], v1, s[36:37] offset:704
	s_waitcnt vmcnt(28)
	v_mfma_f32_16x16x32_bf16 v[32:35], v[136:139], v[128:131], v[32:35]
	v_mfma_f32_16x16x32_bf16 v[52:55], v[136:139], v[132:135], v[52:55]
	v_mfma_f32_16x16x32_bf16 v[36:39], v[140:143], v[128:131], v[36:39]
	v_mfma_f32_16x16x32_bf16 v[56:59], v[140:143], v[132:135], v[56:59]
	v_mfma_f32_16x16x32_bf16 v[40:43], v[144:147], v[128:131], v[40:43]
	v_mfma_f32_16x16x32_bf16 v[60:63], v[144:147], v[132:135], v[60:63]
	v_mfma_f32_16x16x32_bf16 v[44:47], v[148:151], v[128:131], v[44:47]
	v_mfma_f32_16x16x32_bf16 v[64:67], v[148:151], v[132:135], v[64:67]
	v_mfma_f32_16x16x32_bf16 v[48:51], v[152:155], v[128:131], v[48:51]
	v_mfma_f32_16x16x32_bf16 v[68:71], v[152:155], v[132:135], v[68:71]
	global_load_dwordx4 v[128:131], v1, s[8:9] offset:768
	global_load_dwordx4 v[132:135], v1, s[16:17] offset:768
	global_load_dwordx4 v[136:139], v1, s[18:19] offset:768
	global_load_dwordx4 v[140:143], v1, s[28:29] offset:768
	global_load_dwordx4 v[144:147], v1, s[30:31] offset:768
	global_load_dwordx4 v[148:151], v1, s[34:35] offset:768
	global_load_dwordx4 v[152:155], v1, s[36:37] offset:768
	s_waitcnt vmcnt(28)
	v_mfma_f32_16x16x32_bf16 v[32:35], v[176:179], v[156:159], v[32:35]
	v_mfma_f32_16x16x32_bf16 v[52:55], v[176:179], v[172:175], v[52:55]
	v_mfma_f32_16x16x32_bf16 v[36:39], v[180:183], v[156:159], v[36:39]
	v_mfma_f32_16x16x32_bf16 v[56:59], v[180:183], v[172:175], v[56:59]
	v_mfma_f32_16x16x32_bf16 v[40:43], v[184:187], v[156:159], v[40:43]
	v_mfma_f32_16x16x32_bf16 v[60:63], v[184:187], v[172:175], v[60:63]
	v_mfma_f32_16x16x32_bf16 v[44:47], v[196:199], v[156:159], v[44:47]
	v_mfma_f32_16x16x32_bf16 v[64:67], v[196:199], v[172:175], v[64:67]
	v_mfma_f32_16x16x32_bf16 v[48:51], v[200:203], v[156:159], v[48:51]
	v_mfma_f32_16x16x32_bf16 v[68:71], v[200:203], v[172:175], v[68:71]
	global_load_dwordx4 v[156:159], v1, s[8:9] offset:832
	global_load_dwordx4 v[172:175], v1, s[16:17] offset:832
	global_load_dwordx4 v[176:179], v1, s[18:19] offset:832
	global_load_dwordx4 v[180:183], v1, s[28:29] offset:832
	global_load_dwordx4 v[184:187], v1, s[30:31] offset:832
	global_load_dwordx4 v[196:199], v1, s[34:35] offset:832
	global_load_dwordx4 v[200:203], v1, s[36:37] offset:832
	s_waitcnt vmcnt(28)
	v_mfma_f32_16x16x32_bf16 v[32:35], v[212:215], v[204:207], v[32:35]
	v_mfma_f32_16x16x32_bf16 v[52:55], v[212:215], v[208:211], v[52:55]
	v_mfma_f32_16x16x32_bf16 v[36:39], v[234:237], v[204:207], v[36:39]
	v_mfma_f32_16x16x32_bf16 v[56:59], v[234:237], v[208:211], v[56:59]
	v_mfma_f32_16x16x32_bf16 v[40:43], v[238:241], v[204:207], v[40:43]
	v_mfma_f32_16x16x32_bf16 v[60:63], v[238:241], v[208:211], v[60:63]
	v_mfma_f32_16x16x32_bf16 v[44:47], v[242:245], v[204:207], v[44:47]
	v_mfma_f32_16x16x32_bf16 v[64:67], v[242:245], v[208:211], v[64:67]
	v_mfma_f32_16x16x32_bf16 v[48:51], v[246:249], v[204:207], v[48:51]
	v_mfma_f32_16x16x32_bf16 v[68:71], v[246:249], v[208:211], v[68:71]
	global_load_dwordx4 v[204:207], v1, s[8:9] offset:896
	global_load_dwordx4 v[208:211], v1, s[16:17] offset:896
	global_load_dwordx4 v[212:215], v1, s[18:19] offset:896
	global_load_dwordx4 v[234:237], v1, s[28:29] offset:896
	global_load_dwordx4 v[238:241], v1, s[30:31] offset:896
	global_load_dwordx4 v[242:245], v1, s[34:35] offset:896
	global_load_dwordx4 v[246:249], v1, s[36:37] offset:896
	s_waitcnt vmcnt(28)
	v_mfma_f32_16x16x32_bf16 v[32:35], v[80:83], v[72:75], v[32:35]
	v_mfma_f32_16x16x32_bf16 v[52:55], v[80:83], v[76:79], v[52:55]
	v_mfma_f32_16x16x32_bf16 v[36:39], v[84:87], v[72:75], v[36:39]
	v_mfma_f32_16x16x32_bf16 v[56:59], v[84:87], v[76:79], v[56:59]
	v_mfma_f32_16x16x32_bf16 v[40:43], v[88:91], v[72:75], v[40:43]
	v_mfma_f32_16x16x32_bf16 v[60:63], v[88:91], v[76:79], v[60:63]
	v_mfma_f32_16x16x32_bf16 v[44:47], v[92:95], v[72:75], v[44:47]
	v_mfma_f32_16x16x32_bf16 v[64:67], v[92:95], v[76:79], v[64:67]
	v_mfma_f32_16x16x32_bf16 v[48:51], v[96:99], v[72:75], v[48:51]
	v_mfma_f32_16x16x32_bf16 v[68:71], v[96:99], v[76:79], v[68:71]
	global_load_dwordx4 v[72:75], v1, s[8:9] offset:960
	global_load_dwordx4 v[76:79], v1, s[16:17] offset:960
	global_load_dwordx4 v[80:83], v1, s[18:19] offset:960
	global_load_dwordx4 v[84:87], v1, s[28:29] offset:960
	global_load_dwordx4 v[88:91], v1, s[30:31] offset:960
	global_load_dwordx4 v[92:95], v1, s[34:35] offset:960
	global_load_dwordx4 v[96:99], v1, s[36:37] offset:960
	s_waitcnt vmcnt(28)
	v_mfma_f32_16x16x32_bf16 v[32:35], v[108:111], v[100:103], v[32:35]
	v_mfma_f32_16x16x32_bf16 v[52:55], v[108:111], v[104:107], v[52:55]
	v_mfma_f32_16x16x32_bf16 v[36:39], v[112:115], v[100:103], v[36:39]
	v_mfma_f32_16x16x32_bf16 v[56:59], v[112:115], v[104:107], v[56:59]
	v_mfma_f32_16x16x32_bf16 v[40:43], v[116:119], v[100:103], v[40:43]
	v_mfma_f32_16x16x32_bf16 v[60:63], v[116:119], v[104:107], v[60:63]
	v_mfma_f32_16x16x32_bf16 v[44:47], v[120:123], v[100:103], v[44:47]
	v_mfma_f32_16x16x32_bf16 v[64:67], v[120:123], v[104:107], v[64:67]
	v_mfma_f32_16x16x32_bf16 v[48:51], v[124:127], v[100:103], v[48:51]
	v_mfma_f32_16x16x32_bf16 v[68:71], v[124:127], v[104:107], v[68:71]
	global_load_dwordx4 v[100:103], v1, s[8:9] offset:1024
	global_load_dwordx4 v[104:107], v1, s[16:17] offset:1024
	global_load_dwordx4 v[108:111], v1, s[18:19] offset:1024
	global_load_dwordx4 v[112:115], v1, s[28:29] offset:1024
	global_load_dwordx4 v[116:119], v1, s[30:31] offset:1024
	global_load_dwordx4 v[120:123], v1, s[34:35] offset:1024
	global_load_dwordx4 v[124:127], v1, s[36:37] offset:1024
	s_waitcnt vmcnt(28)
	v_mfma_f32_16x16x32_bf16 v[32:35], v[136:139], v[128:131], v[32:35]
	v_mfma_f32_16x16x32_bf16 v[52:55], v[136:139], v[132:135], v[52:55]
	v_mfma_f32_16x16x32_bf16 v[36:39], v[140:143], v[128:131], v[36:39]
	v_mfma_f32_16x16x32_bf16 v[56:59], v[140:143], v[132:135], v[56:59]
	v_mfma_f32_16x16x32_bf16 v[40:43], v[144:147], v[128:131], v[40:43]
	v_mfma_f32_16x16x32_bf16 v[60:63], v[144:147], v[132:135], v[60:63]
	v_mfma_f32_16x16x32_bf16 v[44:47], v[148:151], v[128:131], v[44:47]
	v_mfma_f32_16x16x32_bf16 v[64:67], v[148:151], v[132:135], v[64:67]
	v_mfma_f32_16x16x32_bf16 v[48:51], v[152:155], v[128:131], v[48:51]
	v_mfma_f32_16x16x32_bf16 v[68:71], v[152:155], v[132:135], v[68:71]
	global_load_dwordx4 v[128:131], v1, s[8:9] offset:1088
	global_load_dwordx4 v[132:135], v1, s[16:17] offset:1088
	global_load_dwordx4 v[136:139], v1, s[18:19] offset:1088
	global_load_dwordx4 v[140:143], v1, s[28:29] offset:1088
	global_load_dwordx4 v[144:147], v1, s[30:31] offset:1088
	global_load_dwordx4 v[148:151], v1, s[34:35] offset:1088
	global_load_dwordx4 v[152:155], v1, s[36:37] offset:1088
	s_waitcnt vmcnt(28)
	v_mfma_f32_16x16x32_bf16 v[32:35], v[176:179], v[156:159], v[32:35]
	v_mfma_f32_16x16x32_bf16 v[52:55], v[176:179], v[172:175], v[52:55]
	v_mfma_f32_16x16x32_bf16 v[36:39], v[180:183], v[156:159], v[36:39]
	v_mfma_f32_16x16x32_bf16 v[56:59], v[180:183], v[172:175], v[56:59]
	v_mfma_f32_16x16x32_bf16 v[40:43], v[184:187], v[156:159], v[40:43]
	v_mfma_f32_16x16x32_bf16 v[60:63], v[184:187], v[172:175], v[60:63]
	v_mfma_f32_16x16x32_bf16 v[44:47], v[196:199], v[156:159], v[44:47]
	v_mfma_f32_16x16x32_bf16 v[64:67], v[196:199], v[172:175], v[64:67]
	v_mfma_f32_16x16x32_bf16 v[48:51], v[200:203], v[156:159], v[48:51]
	v_mfma_f32_16x16x32_bf16 v[68:71], v[200:203], v[172:175], v[68:71]
	global_load_dwordx4 v[156:159], v1, s[8:9] offset:1152
	global_load_dwordx4 v[172:175], v1, s[16:17] offset:1152
	global_load_dwordx4 v[176:179], v1, s[18:19] offset:1152
	global_load_dwordx4 v[180:183], v1, s[28:29] offset:1152
	global_load_dwordx4 v[184:187], v1, s[30:31] offset:1152
	global_load_dwordx4 v[196:199], v1, s[34:35] offset:1152
	global_load_dwordx4 v[200:203], v1, s[36:37] offset:1152
	s_waitcnt vmcnt(28)
	v_mfma_f32_16x16x32_bf16 v[32:35], v[212:215], v[204:207], v[32:35]
	v_mfma_f32_16x16x32_bf16 v[52:55], v[212:215], v[208:211], v[52:55]
	v_mfma_f32_16x16x32_bf16 v[36:39], v[234:237], v[204:207], v[36:39]
	v_mfma_f32_16x16x32_bf16 v[56:59], v[234:237], v[208:211], v[56:59]
	v_mfma_f32_16x16x32_bf16 v[40:43], v[238:241], v[204:207], v[40:43]
	v_mfma_f32_16x16x32_bf16 v[60:63], v[238:241], v[208:211], v[60:63]
	v_mfma_f32_16x16x32_bf16 v[44:47], v[242:245], v[204:207], v[44:47]
	v_mfma_f32_16x16x32_bf16 v[64:67], v[242:245], v[208:211], v[64:67]
	v_mfma_f32_16x16x32_bf16 v[48:51], v[246:249], v[204:207], v[48:51]
	v_mfma_f32_16x16x32_bf16 v[68:71], v[246:249], v[208:211], v[68:71]
	global_load_dwordx4 v[204:207], v1, s[8:9] offset:1216
	global_load_dwordx4 v[208:211], v1, s[16:17] offset:1216
	global_load_dwordx4 v[212:215], v1, s[18:19] offset:1216
	global_load_dwordx4 v[234:237], v1, s[28:29] offset:1216
	global_load_dwordx4 v[238:241], v1, s[30:31] offset:1216
	global_load_dwordx4 v[242:245], v1, s[34:35] offset:1216
	global_load_dwordx4 v[246:249], v1, s[36:37] offset:1216
	s_waitcnt vmcnt(28)
	v_mfma_f32_16x16x32_bf16 v[32:35], v[80:83], v[72:75], v[32:35]
	v_mfma_f32_16x16x32_bf16 v[52:55], v[80:83], v[76:79], v[52:55]
	v_mfma_f32_16x16x32_bf16 v[36:39], v[84:87], v[72:75], v[36:39]
	v_mfma_f32_16x16x32_bf16 v[56:59], v[84:87], v[76:79], v[56:59]
	v_mfma_f32_16x16x32_bf16 v[40:43], v[88:91], v[72:75], v[40:43]
	v_mfma_f32_16x16x32_bf16 v[60:63], v[88:91], v[76:79], v[60:63]
	v_mfma_f32_16x16x32_bf16 v[44:47], v[92:95], v[72:75], v[44:47]
	v_mfma_f32_16x16x32_bf16 v[64:67], v[92:95], v[76:79], v[64:67]
	v_mfma_f32_16x16x32_bf16 v[48:51], v[96:99], v[72:75], v[48:51]
	v_mfma_f32_16x16x32_bf16 v[68:71], v[96:99], v[76:79], v[68:71]
	global_load_dwordx4 v[72:75], v1, s[8:9] offset:1280
	global_load_dwordx4 v[76:79], v1, s[16:17] offset:1280
	global_load_dwordx4 v[80:83], v1, s[18:19] offset:1280
	global_load_dwordx4 v[84:87], v1, s[28:29] offset:1280
	global_load_dwordx4 v[88:91], v1, s[30:31] offset:1280
	global_load_dwordx4 v[92:95], v1, s[34:35] offset:1280
	global_load_dwordx4 v[96:99], v1, s[36:37] offset:1280
	s_waitcnt vmcnt(28)
	v_mfma_f32_16x16x32_bf16 v[32:35], v[108:111], v[100:103], v[32:35]
	v_mfma_f32_16x16x32_bf16 v[52:55], v[108:111], v[104:107], v[52:55]
	v_mfma_f32_16x16x32_bf16 v[36:39], v[112:115], v[100:103], v[36:39]
	v_mfma_f32_16x16x32_bf16 v[56:59], v[112:115], v[104:107], v[56:59]
	v_mfma_f32_16x16x32_bf16 v[40:43], v[116:119], v[100:103], v[40:43]
	v_mfma_f32_16x16x32_bf16 v[60:63], v[116:119], v[104:107], v[60:63]
	v_mfma_f32_16x16x32_bf16 v[44:47], v[120:123], v[100:103], v[44:47]
	v_mfma_f32_16x16x32_bf16 v[64:67], v[120:123], v[104:107], v[64:67]
	v_mfma_f32_16x16x32_bf16 v[48:51], v[124:127], v[100:103], v[48:51]
	v_mfma_f32_16x16x32_bf16 v[68:71], v[124:127], v[104:107], v[68:71]
	global_load_dwordx4 v[100:103], v1, s[8:9] offset:1344
	global_load_dwordx4 v[104:107], v1, s[16:17] offset:1344
	global_load_dwordx4 v[108:111], v1, s[18:19] offset:1344
	global_load_dwordx4 v[112:115], v1, s[28:29] offset:1344
	global_load_dwordx4 v[116:119], v1, s[30:31] offset:1344
	global_load_dwordx4 v[120:123], v1, s[34:35] offset:1344
	global_load_dwordx4 v[124:127], v1, s[36:37] offset:1344
	s_waitcnt vmcnt(28)
	v_mfma_f32_16x16x32_bf16 v[32:35], v[136:139], v[128:131], v[32:35]
	v_mfma_f32_16x16x32_bf16 v[52:55], v[136:139], v[132:135], v[52:55]
	v_mfma_f32_16x16x32_bf16 v[36:39], v[140:143], v[128:131], v[36:39]
	v_mfma_f32_16x16x32_bf16 v[56:59], v[140:143], v[132:135], v[56:59]
	v_mfma_f32_16x16x32_bf16 v[40:43], v[144:147], v[128:131], v[40:43]
	v_mfma_f32_16x16x32_bf16 v[60:63], v[144:147], v[132:135], v[60:63]
	v_mfma_f32_16x16x32_bf16 v[44:47], v[148:151], v[128:131], v[44:47]
	v_mfma_f32_16x16x32_bf16 v[64:67], v[148:151], v[132:135], v[64:67]
	v_mfma_f32_16x16x32_bf16 v[48:51], v[152:155], v[128:131], v[48:51]
	v_mfma_f32_16x16x32_bf16 v[68:71], v[152:155], v[132:135], v[68:71]
	global_load_dwordx4 v[128:131], v1, s[8:9] offset:1408
	global_load_dwordx4 v[132:135], v1, s[16:17] offset:1408
	global_load_dwordx4 v[136:139], v1, s[18:19] offset:1408
	global_load_dwordx4 v[140:143], v1, s[28:29] offset:1408
	global_load_dwordx4 v[144:147], v1, s[30:31] offset:1408
	global_load_dwordx4 v[148:151], v1, s[34:35] offset:1408
	global_load_dwordx4 v[152:155], v1, s[36:37] offset:1408
	s_waitcnt vmcnt(28)
	v_mfma_f32_16x16x32_bf16 v[32:35], v[176:179], v[156:159], v[32:35]
	v_mfma_f32_16x16x32_bf16 v[52:55], v[176:179], v[172:175], v[52:55]
	v_mfma_f32_16x16x32_bf16 v[36:39], v[180:183], v[156:159], v[36:39]
	v_mfma_f32_16x16x32_bf16 v[56:59], v[180:183], v[172:175], v[56:59]
	v_mfma_f32_16x16x32_bf16 v[40:43], v[184:187], v[156:159], v[40:43]
	v_mfma_f32_16x16x32_bf16 v[60:63], v[184:187], v[172:175], v[60:63]
	v_mfma_f32_16x16x32_bf16 v[44:47], v[196:199], v[156:159], v[44:47]
	v_mfma_f32_16x16x32_bf16 v[64:67], v[196:199], v[172:175], v[64:67]
	v_mfma_f32_16x16x32_bf16 v[48:51], v[200:203], v[156:159], v[48:51]
	v_mfma_f32_16x16x32_bf16 v[68:71], v[200:203], v[172:175], v[68:71]
	global_load_dwordx4 v[156:159], v1, s[8:9] offset:1472
	global_load_dwordx4 v[172:175], v1, s[16:17] offset:1472
	global_load_dwordx4 v[176:179], v1, s[18:19] offset:1472
	global_load_dwordx4 v[180:183], v1, s[28:29] offset:1472
	global_load_dwordx4 v[184:187], v1, s[30:31] offset:1472
	global_load_dwordx4 v[196:199], v1, s[34:35] offset:1472
	global_load_dwordx4 v[200:203], v1, s[36:37] offset:1472
	s_waitcnt vmcnt(28)
	v_mfma_f32_16x16x32_bf16 v[32:35], v[212:215], v[204:207], v[32:35]
	v_mfma_f32_16x16x32_bf16 v[52:55], v[212:215], v[208:211], v[52:55]
	v_mfma_f32_16x16x32_bf16 v[36:39], v[234:237], v[204:207], v[36:39]
	v_mfma_f32_16x16x32_bf16 v[56:59], v[234:237], v[208:211], v[56:59]
	v_mfma_f32_16x16x32_bf16 v[40:43], v[238:241], v[204:207], v[40:43]
	v_mfma_f32_16x16x32_bf16 v[60:63], v[238:241], v[208:211], v[60:63]
	v_mfma_f32_16x16x32_bf16 v[44:47], v[242:245], v[204:207], v[44:47]
	v_mfma_f32_16x16x32_bf16 v[64:67], v[242:245], v[208:211], v[64:67]
	v_mfma_f32_16x16x32_bf16 v[48:51], v[246:249], v[204:207], v[48:51]
	v_mfma_f32_16x16x32_bf16 v[68:71], v[246:249], v[208:211], v[68:71]
	global_load_dwordx4 v[204:207], v1, s[8:9] offset:1536
	global_load_dwordx4 v[208:211], v1, s[16:17] offset:1536
	global_load_dwordx4 v[212:215], v1, s[18:19] offset:1536
	global_load_dwordx4 v[234:237], v1, s[28:29] offset:1536
	global_load_dwordx4 v[238:241], v1, s[30:31] offset:1536
	global_load_dwordx4 v[242:245], v1, s[34:35] offset:1536
	global_load_dwordx4 v[246:249], v1, s[36:37] offset:1536
	s_waitcnt vmcnt(28)
	v_mfma_f32_16x16x32_bf16 v[32:35], v[80:83], v[72:75], v[32:35]
	v_mfma_f32_16x16x32_bf16 v[52:55], v[80:83], v[76:79], v[52:55]
	v_mfma_f32_16x16x32_bf16 v[36:39], v[84:87], v[72:75], v[36:39]
	v_mfma_f32_16x16x32_bf16 v[56:59], v[84:87], v[76:79], v[56:59]
	v_mfma_f32_16x16x32_bf16 v[40:43], v[88:91], v[72:75], v[40:43]
	v_mfma_f32_16x16x32_bf16 v[60:63], v[88:91], v[76:79], v[60:63]
	v_mfma_f32_16x16x32_bf16 v[44:47], v[92:95], v[72:75], v[44:47]
	v_mfma_f32_16x16x32_bf16 v[64:67], v[92:95], v[76:79], v[64:67]
	v_mfma_f32_16x16x32_bf16 v[48:51], v[96:99], v[72:75], v[48:51]
	v_mfma_f32_16x16x32_bf16 v[68:71], v[96:99], v[76:79], v[68:71]
	global_load_dwordx4 v[72:75], v1, s[8:9] offset:1600
	global_load_dwordx4 v[76:79], v1, s[16:17] offset:1600
	global_load_dwordx4 v[80:83], v1, s[18:19] offset:1600
	global_load_dwordx4 v[84:87], v1, s[28:29] offset:1600
	global_load_dwordx4 v[88:91], v1, s[30:31] offset:1600
	global_load_dwordx4 v[92:95], v1, s[34:35] offset:1600
	global_load_dwordx4 v[96:99], v1, s[36:37] offset:1600
	s_waitcnt vmcnt(28)
	v_mfma_f32_16x16x32_bf16 v[32:35], v[108:111], v[100:103], v[32:35]
	v_mfma_f32_16x16x32_bf16 v[52:55], v[108:111], v[104:107], v[52:55]
	v_mfma_f32_16x16x32_bf16 v[36:39], v[112:115], v[100:103], v[36:39]
	v_mfma_f32_16x16x32_bf16 v[56:59], v[112:115], v[104:107], v[56:59]
	v_mfma_f32_16x16x32_bf16 v[40:43], v[116:119], v[100:103], v[40:43]
	v_mfma_f32_16x16x32_bf16 v[60:63], v[116:119], v[104:107], v[60:63]
	v_mfma_f32_16x16x32_bf16 v[44:47], v[120:123], v[100:103], v[44:47]
	v_mfma_f32_16x16x32_bf16 v[64:67], v[120:123], v[104:107], v[64:67]
	v_mfma_f32_16x16x32_bf16 v[48:51], v[124:127], v[100:103], v[48:51]
	v_mfma_f32_16x16x32_bf16 v[68:71], v[124:127], v[104:107], v[68:71]
	global_load_dwordx4 v[100:103], v1, s[8:9] offset:1664
	global_load_dwordx4 v[104:107], v1, s[16:17] offset:1664
	global_load_dwordx4 v[108:111], v1, s[18:19] offset:1664
	global_load_dwordx4 v[112:115], v1, s[28:29] offset:1664
	global_load_dwordx4 v[116:119], v1, s[30:31] offset:1664
	global_load_dwordx4 v[120:123], v1, s[34:35] offset:1664
	global_load_dwordx4 v[124:127], v1, s[36:37] offset:1664
	s_waitcnt vmcnt(28)
	v_mfma_f32_16x16x32_bf16 v[32:35], v[136:139], v[128:131], v[32:35]
	v_mfma_f32_16x16x32_bf16 v[52:55], v[136:139], v[132:135], v[52:55]
	v_mfma_f32_16x16x32_bf16 v[36:39], v[140:143], v[128:131], v[36:39]
	v_mfma_f32_16x16x32_bf16 v[56:59], v[140:143], v[132:135], v[56:59]
	v_mfma_f32_16x16x32_bf16 v[40:43], v[144:147], v[128:131], v[40:43]
	v_mfma_f32_16x16x32_bf16 v[60:63], v[144:147], v[132:135], v[60:63]
	v_mfma_f32_16x16x32_bf16 v[44:47], v[148:151], v[128:131], v[44:47]
	v_mfma_f32_16x16x32_bf16 v[64:67], v[148:151], v[132:135], v[64:67]
	v_mfma_f32_16x16x32_bf16 v[48:51], v[152:155], v[128:131], v[48:51]
	v_mfma_f32_16x16x32_bf16 v[68:71], v[152:155], v[132:135], v[68:71]
	global_load_dwordx4 v[128:131], v1, s[8:9] offset:1728
	global_load_dwordx4 v[132:135], v1, s[16:17] offset:1728
	global_load_dwordx4 v[136:139], v1, s[18:19] offset:1728
	global_load_dwordx4 v[140:143], v1, s[28:29] offset:1728
	global_load_dwordx4 v[144:147], v1, s[30:31] offset:1728
	global_load_dwordx4 v[148:151], v1, s[34:35] offset:1728
	global_load_dwordx4 v[152:155], v1, s[36:37] offset:1728
	s_waitcnt vmcnt(28)
	v_mfma_f32_16x16x32_bf16 v[32:35], v[176:179], v[156:159], v[32:35]
	v_mfma_f32_16x16x32_bf16 v[52:55], v[176:179], v[172:175], v[52:55]
	v_mfma_f32_16x16x32_bf16 v[36:39], v[180:183], v[156:159], v[36:39]
	v_mfma_f32_16x16x32_bf16 v[56:59], v[180:183], v[172:175], v[56:59]
	v_mfma_f32_16x16x32_bf16 v[40:43], v[184:187], v[156:159], v[40:43]
	v_mfma_f32_16x16x32_bf16 v[60:63], v[184:187], v[172:175], v[60:63]
	v_mfma_f32_16x16x32_bf16 v[44:47], v[196:199], v[156:159], v[44:47]
	v_mfma_f32_16x16x32_bf16 v[64:67], v[196:199], v[172:175], v[64:67]
	v_mfma_f32_16x16x32_bf16 v[48:51], v[200:203], v[156:159], v[48:51]
	v_mfma_f32_16x16x32_bf16 v[68:71], v[200:203], v[172:175], v[68:71]
	global_load_dwordx4 v[156:159], v1, s[8:9] offset:1792
	global_load_dwordx4 v[172:175], v1, s[16:17] offset:1792
	global_load_dwordx4 v[176:179], v1, s[18:19] offset:1792
	global_load_dwordx4 v[180:183], v1, s[28:29] offset:1792
	global_load_dwordx4 v[184:187], v1, s[30:31] offset:1792
	global_load_dwordx4 v[196:199], v1, s[34:35] offset:1792
	global_load_dwordx4 v[200:203], v1, s[36:37] offset:1792
	s_waitcnt vmcnt(28)
	v_mfma_f32_16x16x32_bf16 v[32:35], v[212:215], v[204:207], v[32:35]
	v_mfma_f32_16x16x32_bf16 v[52:55], v[212:215], v[208:211], v[52:55]
	v_mfma_f32_16x16x32_bf16 v[36:39], v[234:237], v[204:207], v[36:39]
	v_mfma_f32_16x16x32_bf16 v[56:59], v[234:237], v[208:211], v[56:59]
	v_mfma_f32_16x16x32_bf16 v[40:43], v[238:241], v[204:207], v[40:43]
	v_mfma_f32_16x16x32_bf16 v[60:63], v[238:241], v[208:211], v[60:63]
	v_mfma_f32_16x16x32_bf16 v[44:47], v[242:245], v[204:207], v[44:47]
	v_mfma_f32_16x16x32_bf16 v[64:67], v[242:245], v[208:211], v[64:67]
	v_mfma_f32_16x16x32_bf16 v[48:51], v[246:249], v[204:207], v[48:51]
	v_mfma_f32_16x16x32_bf16 v[68:71], v[246:249], v[208:211], v[68:71]
	global_load_dwordx4 v[204:207], v1, s[8:9] offset:1856
	global_load_dwordx4 v[208:211], v1, s[16:17] offset:1856
	global_load_dwordx4 v[212:215], v1, s[18:19] offset:1856
	global_load_dwordx4 v[234:237], v1, s[28:29] offset:1856
	global_load_dwordx4 v[238:241], v1, s[30:31] offset:1856
	global_load_dwordx4 v[242:245], v1, s[34:35] offset:1856
	global_load_dwordx4 v[246:249], v1, s[36:37] offset:1856
	s_waitcnt vmcnt(28)
	v_mfma_f32_16x16x32_bf16 v[32:35], v[80:83], v[72:75], v[32:35]
	v_mfma_f32_16x16x32_bf16 v[52:55], v[80:83], v[76:79], v[52:55]
	v_mfma_f32_16x16x32_bf16 v[36:39], v[84:87], v[72:75], v[36:39]
	v_mfma_f32_16x16x32_bf16 v[56:59], v[84:87], v[76:79], v[56:59]
	v_mfma_f32_16x16x32_bf16 v[40:43], v[88:91], v[72:75], v[40:43]
	v_mfma_f32_16x16x32_bf16 v[60:63], v[88:91], v[76:79], v[60:63]
	v_mfma_f32_16x16x32_bf16 v[44:47], v[92:95], v[72:75], v[44:47]
	v_mfma_f32_16x16x32_bf16 v[64:67], v[92:95], v[76:79], v[64:67]
	v_mfma_f32_16x16x32_bf16 v[48:51], v[96:99], v[72:75], v[48:51]
	v_mfma_f32_16x16x32_bf16 v[68:71], v[96:99], v[76:79], v[68:71]
	global_load_dwordx4 v[72:75], v1, s[8:9] offset:1920
	global_load_dwordx4 v[76:79], v1, s[16:17] offset:1920
	global_load_dwordx4 v[80:83], v1, s[18:19] offset:1920
	global_load_dwordx4 v[84:87], v1, s[28:29] offset:1920
	global_load_dwordx4 v[88:91], v1, s[30:31] offset:1920
	global_load_dwordx4 v[92:95], v1, s[34:35] offset:1920
	global_load_dwordx4 v[96:99], v1, s[36:37] offset:1920
	s_waitcnt vmcnt(28)
	v_mfma_f32_16x16x32_bf16 v[32:35], v[108:111], v[100:103], v[32:35]
	v_mfma_f32_16x16x32_bf16 v[52:55], v[108:111], v[104:107], v[52:55]
	v_mfma_f32_16x16x32_bf16 v[36:39], v[112:115], v[100:103], v[36:39]
	v_mfma_f32_16x16x32_bf16 v[56:59], v[112:115], v[104:107], v[56:59]
	v_mfma_f32_16x16x32_bf16 v[40:43], v[116:119], v[100:103], v[40:43]
	v_mfma_f32_16x16x32_bf16 v[60:63], v[116:119], v[104:107], v[60:63]
	v_mfma_f32_16x16x32_bf16 v[44:47], v[120:123], v[100:103], v[44:47]
	v_mfma_f32_16x16x32_bf16 v[64:67], v[120:123], v[104:107], v[64:67]
	v_mfma_f32_16x16x32_bf16 v[48:51], v[124:127], v[100:103], v[48:51]
	v_mfma_f32_16x16x32_bf16 v[68:71], v[124:127], v[104:107], v[68:71]
	global_load_dwordx4 v[100:103], v1, s[8:9] offset:1984
	global_load_dwordx4 v[104:107], v1, s[16:17] offset:1984
	global_load_dwordx4 v[108:111], v1, s[18:19] offset:1984
	global_load_dwordx4 v[112:115], v1, s[28:29] offset:1984
	global_load_dwordx4 v[116:119], v1, s[30:31] offset:1984
	global_load_dwordx4 v[120:123], v1, s[34:35] offset:1984
	global_load_dwordx4 v[124:127], v1, s[36:37] offset:1984
	s_waitcnt vmcnt(28)
	v_mfma_f32_16x16x32_bf16 v[32:35], v[136:139], v[128:131], v[32:35]
	v_mfma_f32_16x16x32_bf16 v[52:55], v[136:139], v[132:135], v[52:55]
	v_mfma_f32_16x16x32_bf16 v[36:39], v[140:143], v[128:131], v[36:39]
	v_mfma_f32_16x16x32_bf16 v[56:59], v[140:143], v[132:135], v[56:59]
	v_mfma_f32_16x16x32_bf16 v[40:43], v[144:147], v[128:131], v[40:43]
	v_mfma_f32_16x16x32_bf16 v[60:63], v[144:147], v[132:135], v[60:63]
	v_mfma_f32_16x16x32_bf16 v[44:47], v[148:151], v[128:131], v[44:47]
	v_mfma_f32_16x16x32_bf16 v[64:67], v[148:151], v[132:135], v[64:67]
	v_mfma_f32_16x16x32_bf16 v[48:51], v[152:155], v[128:131], v[48:51]
	v_mfma_f32_16x16x32_bf16 v[68:71], v[152:155], v[132:135], v[68:71]
	global_load_dwordx4 v[128:131], v1, s[8:9] offset:2048
	global_load_dwordx4 v[132:135], v1, s[16:17] offset:2048
	global_load_dwordx4 v[136:139], v1, s[18:19] offset:2048
	global_load_dwordx4 v[140:143], v1, s[28:29] offset:2048
	global_load_dwordx4 v[144:147], v1, s[30:31] offset:2048
	global_load_dwordx4 v[148:151], v1, s[34:35] offset:2048
	global_load_dwordx4 v[152:155], v1, s[36:37] offset:2048
	s_waitcnt vmcnt(28)
	v_mfma_f32_16x16x32_bf16 v[32:35], v[176:179], v[156:159], v[32:35]
	v_mfma_f32_16x16x32_bf16 v[52:55], v[176:179], v[172:175], v[52:55]
	v_mfma_f32_16x16x32_bf16 v[36:39], v[180:183], v[156:159], v[36:39]
	v_mfma_f32_16x16x32_bf16 v[56:59], v[180:183], v[172:175], v[56:59]
	v_mfma_f32_16x16x32_bf16 v[40:43], v[184:187], v[156:159], v[40:43]
	v_mfma_f32_16x16x32_bf16 v[60:63], v[184:187], v[172:175], v[60:63]
	v_mfma_f32_16x16x32_bf16 v[44:47], v[196:199], v[156:159], v[44:47]
	v_mfma_f32_16x16x32_bf16 v[64:67], v[196:199], v[172:175], v[64:67]
	v_mfma_f32_16x16x32_bf16 v[48:51], v[200:203], v[156:159], v[48:51]
	v_mfma_f32_16x16x32_bf16 v[68:71], v[200:203], v[172:175], v[68:71]
	global_load_dwordx4 v[156:159], v1, s[8:9] offset:2112
	global_load_dwordx4 v[172:175], v1, s[16:17] offset:2112
	global_load_dwordx4 v[176:179], v1, s[18:19] offset:2112
	global_load_dwordx4 v[180:183], v1, s[28:29] offset:2112
	global_load_dwordx4 v[184:187], v1, s[30:31] offset:2112
	global_load_dwordx4 v[196:199], v1, s[34:35] offset:2112
	global_load_dwordx4 v[200:203], v1, s[36:37] offset:2112
	s_waitcnt vmcnt(28)
	v_mfma_f32_16x16x32_bf16 v[32:35], v[212:215], v[204:207], v[32:35]
	v_mfma_f32_16x16x32_bf16 v[52:55], v[212:215], v[208:211], v[52:55]
	v_mfma_f32_16x16x32_bf16 v[36:39], v[234:237], v[204:207], v[36:39]
	v_mfma_f32_16x16x32_bf16 v[56:59], v[234:237], v[208:211], v[56:59]
	v_mfma_f32_16x16x32_bf16 v[40:43], v[238:241], v[204:207], v[40:43]
	v_mfma_f32_16x16x32_bf16 v[60:63], v[238:241], v[208:211], v[60:63]
	v_mfma_f32_16x16x32_bf16 v[44:47], v[242:245], v[204:207], v[44:47]
	v_mfma_f32_16x16x32_bf16 v[64:67], v[242:245], v[208:211], v[64:67]
	v_mfma_f32_16x16x32_bf16 v[48:51], v[246:249], v[204:207], v[48:51]
	v_mfma_f32_16x16x32_bf16 v[68:71], v[246:249], v[208:211], v[68:71]
	global_load_dwordx4 v[204:207], v1, s[8:9] offset:2176
	global_load_dwordx4 v[208:211], v1, s[16:17] offset:2176
	global_load_dwordx4 v[212:215], v1, s[18:19] offset:2176
	global_load_dwordx4 v[234:237], v1, s[28:29] offset:2176
	global_load_dwordx4 v[238:241], v1, s[30:31] offset:2176
	global_load_dwordx4 v[242:245], v1, s[34:35] offset:2176
	global_load_dwordx4 v[246:249], v1, s[36:37] offset:2176
	s_waitcnt vmcnt(28)
	v_mfma_f32_16x16x32_bf16 v[32:35], v[80:83], v[72:75], v[32:35]
	v_mfma_f32_16x16x32_bf16 v[52:55], v[80:83], v[76:79], v[52:55]
	v_mfma_f32_16x16x32_bf16 v[36:39], v[84:87], v[72:75], v[36:39]
	v_mfma_f32_16x16x32_bf16 v[56:59], v[84:87], v[76:79], v[56:59]
	v_mfma_f32_16x16x32_bf16 v[40:43], v[88:91], v[72:75], v[40:43]
	v_mfma_f32_16x16x32_bf16 v[60:63], v[88:91], v[76:79], v[60:63]
	v_mfma_f32_16x16x32_bf16 v[44:47], v[92:95], v[72:75], v[44:47]
	v_mfma_f32_16x16x32_bf16 v[64:67], v[92:95], v[76:79], v[64:67]
	v_mfma_f32_16x16x32_bf16 v[48:51], v[96:99], v[72:75], v[48:51]
	v_mfma_f32_16x16x32_bf16 v[68:71], v[96:99], v[76:79], v[68:71]
	global_load_dwordx4 v[72:75], v1, s[8:9] offset:2240
	global_load_dwordx4 v[76:79], v1, s[16:17] offset:2240
	global_load_dwordx4 v[80:83], v1, s[18:19] offset:2240
	global_load_dwordx4 v[84:87], v1, s[28:29] offset:2240
	global_load_dwordx4 v[88:91], v1, s[30:31] offset:2240
	global_load_dwordx4 v[92:95], v1, s[34:35] offset:2240
	global_load_dwordx4 v[96:99], v1, s[36:37] offset:2240
	s_waitcnt vmcnt(28)
	v_mfma_f32_16x16x32_bf16 v[32:35], v[108:111], v[100:103], v[32:35]
	v_mfma_f32_16x16x32_bf16 v[52:55], v[108:111], v[104:107], v[52:55]
	v_mfma_f32_16x16x32_bf16 v[36:39], v[112:115], v[100:103], v[36:39]
	v_mfma_f32_16x16x32_bf16 v[56:59], v[112:115], v[104:107], v[56:59]
	v_mfma_f32_16x16x32_bf16 v[40:43], v[116:119], v[100:103], v[40:43]
	v_mfma_f32_16x16x32_bf16 v[60:63], v[116:119], v[104:107], v[60:63]
	v_mfma_f32_16x16x32_bf16 v[44:47], v[120:123], v[100:103], v[44:47]
	v_mfma_f32_16x16x32_bf16 v[64:67], v[120:123], v[104:107], v[64:67]
	v_mfma_f32_16x16x32_bf16 v[48:51], v[124:127], v[100:103], v[48:51]
	v_mfma_f32_16x16x32_bf16 v[68:71], v[124:127], v[104:107], v[68:71]
	global_load_dwordx4 v[100:103], v1, s[8:9] offset:2304
	global_load_dwordx4 v[104:107], v1, s[16:17] offset:2304
	global_load_dwordx4 v[108:111], v1, s[18:19] offset:2304
	global_load_dwordx4 v[112:115], v1, s[28:29] offset:2304
	global_load_dwordx4 v[116:119], v1, s[30:31] offset:2304
	global_load_dwordx4 v[120:123], v1, s[34:35] offset:2304
	global_load_dwordx4 v[124:127], v1, s[36:37] offset:2304
	s_waitcnt vmcnt(28)
	v_mfma_f32_16x16x32_bf16 v[32:35], v[136:139], v[128:131], v[32:35]
	v_mfma_f32_16x16x32_bf16 v[52:55], v[136:139], v[132:135], v[52:55]
	v_mfma_f32_16x16x32_bf16 v[36:39], v[140:143], v[128:131], v[36:39]
	v_mfma_f32_16x16x32_bf16 v[56:59], v[140:143], v[132:135], v[56:59]
	v_mfma_f32_16x16x32_bf16 v[40:43], v[144:147], v[128:131], v[40:43]
	v_mfma_f32_16x16x32_bf16 v[60:63], v[144:147], v[132:135], v[60:63]
	v_mfma_f32_16x16x32_bf16 v[44:47], v[148:151], v[128:131], v[44:47]
	v_mfma_f32_16x16x32_bf16 v[64:67], v[148:151], v[132:135], v[64:67]
	v_mfma_f32_16x16x32_bf16 v[48:51], v[152:155], v[128:131], v[48:51]
	v_mfma_f32_16x16x32_bf16 v[68:71], v[152:155], v[132:135], v[68:71]
	global_load_dwordx4 v[128:131], v1, s[8:9] offset:2368
	global_load_dwordx4 v[132:135], v1, s[16:17] offset:2368
	global_load_dwordx4 v[136:139], v1, s[18:19] offset:2368
	global_load_dwordx4 v[140:143], v1, s[28:29] offset:2368
	global_load_dwordx4 v[144:147], v1, s[30:31] offset:2368
	global_load_dwordx4 v[148:151], v1, s[34:35] offset:2368
	global_load_dwordx4 v[152:155], v1, s[36:37] offset:2368
	s_waitcnt vmcnt(28)
	v_mfma_f32_16x16x32_bf16 v[32:35], v[176:179], v[156:159], v[32:35]
	v_mfma_f32_16x16x32_bf16 v[52:55], v[176:179], v[172:175], v[52:55]
	v_mfma_f32_16x16x32_bf16 v[36:39], v[180:183], v[156:159], v[36:39]
	v_mfma_f32_16x16x32_bf16 v[56:59], v[180:183], v[172:175], v[56:59]
	v_mfma_f32_16x16x32_bf16 v[40:43], v[184:187], v[156:159], v[40:43]
	v_mfma_f32_16x16x32_bf16 v[60:63], v[184:187], v[172:175], v[60:63]
	v_mfma_f32_16x16x32_bf16 v[44:47], v[196:199], v[156:159], v[44:47]
	v_mfma_f32_16x16x32_bf16 v[64:67], v[196:199], v[172:175], v[64:67]
	v_mfma_f32_16x16x32_bf16 v[48:51], v[200:203], v[156:159], v[48:51]
	v_mfma_f32_16x16x32_bf16 v[68:71], v[200:203], v[172:175], v[68:71]
	global_load_dwordx4 v[156:159], v1, s[8:9] offset:2432
	global_load_dwordx4 v[172:175], v1, s[16:17] offset:2432
	global_load_dwordx4 v[176:179], v1, s[18:19] offset:2432
	global_load_dwordx4 v[180:183], v1, s[28:29] offset:2432
	global_load_dwordx4 v[184:187], v1, s[30:31] offset:2432
	global_load_dwordx4 v[196:199], v1, s[34:35] offset:2432
	global_load_dwordx4 v[200:203], v1, s[36:37] offset:2432
	s_waitcnt vmcnt(28)
	v_mfma_f32_16x16x32_bf16 v[32:35], v[212:215], v[204:207], v[32:35]
	v_mfma_f32_16x16x32_bf16 v[52:55], v[212:215], v[208:211], v[52:55]
	v_mfma_f32_16x16x32_bf16 v[36:39], v[234:237], v[204:207], v[36:39]
	v_mfma_f32_16x16x32_bf16 v[56:59], v[234:237], v[208:211], v[56:59]
	v_mfma_f32_16x16x32_bf16 v[40:43], v[238:241], v[204:207], v[40:43]
	v_mfma_f32_16x16x32_bf16 v[60:63], v[238:241], v[208:211], v[60:63]
	v_mfma_f32_16x16x32_bf16 v[44:47], v[242:245], v[204:207], v[44:47]
	v_mfma_f32_16x16x32_bf16 v[64:67], v[242:245], v[208:211], v[64:67]
	v_mfma_f32_16x16x32_bf16 v[48:51], v[246:249], v[204:207], v[48:51]
	v_mfma_f32_16x16x32_bf16 v[68:71], v[246:249], v[208:211], v[68:71]
	global_load_dwordx4 v[204:207], v1, s[8:9] offset:2496
	global_load_dwordx4 v[208:211], v1, s[16:17] offset:2496
	global_load_dwordx4 v[212:215], v1, s[18:19] offset:2496
	global_load_dwordx4 v[234:237], v1, s[28:29] offset:2496
	global_load_dwordx4 v[238:241], v1, s[30:31] offset:2496
	global_load_dwordx4 v[242:245], v1, s[34:35] offset:2496
	global_load_dwordx4 v[246:249], v1, s[36:37] offset:2496
	s_waitcnt vmcnt(28)
	v_mfma_f32_16x16x32_bf16 v[32:35], v[80:83], v[72:75], v[32:35]
	v_mfma_f32_16x16x32_bf16 v[52:55], v[80:83], v[76:79], v[52:55]
	v_mfma_f32_16x16x32_bf16 v[36:39], v[84:87], v[72:75], v[36:39]
	v_mfma_f32_16x16x32_bf16 v[56:59], v[84:87], v[76:79], v[56:59]
	v_mfma_f32_16x16x32_bf16 v[40:43], v[88:91], v[72:75], v[40:43]
	v_mfma_f32_16x16x32_bf16 v[60:63], v[88:91], v[76:79], v[60:63]
	v_mfma_f32_16x16x32_bf16 v[44:47], v[92:95], v[72:75], v[44:47]
	v_mfma_f32_16x16x32_bf16 v[64:67], v[92:95], v[76:79], v[64:67]
	v_mfma_f32_16x16x32_bf16 v[48:51], v[96:99], v[72:75], v[48:51]
	v_mfma_f32_16x16x32_bf16 v[68:71], v[96:99], v[76:79], v[68:71]
	global_load_dwordx4 v[72:75], v1, s[8:9] offset:2560
	global_load_dwordx4 v[76:79], v1, s[16:17] offset:2560
	global_load_dwordx4 v[80:83], v1, s[18:19] offset:2560
	global_load_dwordx4 v[84:87], v1, s[28:29] offset:2560
	global_load_dwordx4 v[88:91], v1, s[30:31] offset:2560
	global_load_dwordx4 v[92:95], v1, s[34:35] offset:2560
	global_load_dwordx4 v[96:99], v1, s[36:37] offset:2560
	s_waitcnt vmcnt(28)
	v_mfma_f32_16x16x32_bf16 v[32:35], v[108:111], v[100:103], v[32:35]
	v_mfma_f32_16x16x32_bf16 v[52:55], v[108:111], v[104:107], v[52:55]
	v_mfma_f32_16x16x32_bf16 v[36:39], v[112:115], v[100:103], v[36:39]
	v_mfma_f32_16x16x32_bf16 v[56:59], v[112:115], v[104:107], v[56:59]
	v_mfma_f32_16x16x32_bf16 v[40:43], v[116:119], v[100:103], v[40:43]
	v_mfma_f32_16x16x32_bf16 v[60:63], v[116:119], v[104:107], v[60:63]
	v_mfma_f32_16x16x32_bf16 v[44:47], v[120:123], v[100:103], v[44:47]
	v_mfma_f32_16x16x32_bf16 v[64:67], v[120:123], v[104:107], v[64:67]
	v_mfma_f32_16x16x32_bf16 v[48:51], v[124:127], v[100:103], v[48:51]
	v_mfma_f32_16x16x32_bf16 v[68:71], v[124:127], v[104:107], v[68:71]
	global_load_dwordx4 v[100:103], v1, s[8:9] offset:2624
	global_load_dwordx4 v[104:107], v1, s[16:17] offset:2624
	global_load_dwordx4 v[108:111], v1, s[18:19] offset:2624
	global_load_dwordx4 v[112:115], v1, s[28:29] offset:2624
	global_load_dwordx4 v[116:119], v1, s[30:31] offset:2624
	global_load_dwordx4 v[120:123], v1, s[34:35] offset:2624
	global_load_dwordx4 v[124:127], v1, s[36:37] offset:2624
	s_waitcnt vmcnt(28)
	v_mfma_f32_16x16x32_bf16 v[32:35], v[136:139], v[128:131], v[32:35]
	v_mfma_f32_16x16x32_bf16 v[52:55], v[136:139], v[132:135], v[52:55]
	v_mfma_f32_16x16x32_bf16 v[36:39], v[140:143], v[128:131], v[36:39]
	v_mfma_f32_16x16x32_bf16 v[56:59], v[140:143], v[132:135], v[56:59]
	v_mfma_f32_16x16x32_bf16 v[40:43], v[144:147], v[128:131], v[40:43]
	v_mfma_f32_16x16x32_bf16 v[60:63], v[144:147], v[132:135], v[60:63]
	v_mfma_f32_16x16x32_bf16 v[44:47], v[148:151], v[128:131], v[44:47]
	v_mfma_f32_16x16x32_bf16 v[64:67], v[148:151], v[132:135], v[64:67]
	v_mfma_f32_16x16x32_bf16 v[48:51], v[152:155], v[128:131], v[48:51]
	v_mfma_f32_16x16x32_bf16 v[68:71], v[152:155], v[132:135], v[68:71]
	global_load_dwordx4 v[128:131], v1, s[8:9] offset:2688
	global_load_dwordx4 v[132:135], v1, s[16:17] offset:2688
	global_load_dwordx4 v[136:139], v1, s[18:19] offset:2688
	global_load_dwordx4 v[140:143], v1, s[28:29] offset:2688
	global_load_dwordx4 v[144:147], v1, s[30:31] offset:2688
	global_load_dwordx4 v[148:151], v1, s[34:35] offset:2688
	global_load_dwordx4 v[152:155], v1, s[36:37] offset:2688
	s_waitcnt vmcnt(28)
	v_mfma_f32_16x16x32_bf16 v[32:35], v[176:179], v[156:159], v[32:35]
	v_mfma_f32_16x16x32_bf16 v[52:55], v[176:179], v[172:175], v[52:55]
	v_mfma_f32_16x16x32_bf16 v[36:39], v[180:183], v[156:159], v[36:39]
	v_mfma_f32_16x16x32_bf16 v[56:59], v[180:183], v[172:175], v[56:59]
	v_mfma_f32_16x16x32_bf16 v[40:43], v[184:187], v[156:159], v[40:43]
	v_mfma_f32_16x16x32_bf16 v[60:63], v[184:187], v[172:175], v[60:63]
	v_mfma_f32_16x16x32_bf16 v[44:47], v[196:199], v[156:159], v[44:47]
	v_mfma_f32_16x16x32_bf16 v[64:67], v[196:199], v[172:175], v[64:67]
	v_mfma_f32_16x16x32_bf16 v[48:51], v[200:203], v[156:159], v[48:51]
	v_mfma_f32_16x16x32_bf16 v[68:71], v[200:203], v[172:175], v[68:71]
	global_load_dwordx4 v[156:159], v1, s[8:9] offset:2752
	global_load_dwordx4 v[172:175], v1, s[16:17] offset:2752
	global_load_dwordx4 v[176:179], v1, s[18:19] offset:2752
	global_load_dwordx4 v[180:183], v1, s[28:29] offset:2752
	global_load_dwordx4 v[184:187], v1, s[30:31] offset:2752
	global_load_dwordx4 v[196:199], v1, s[34:35] offset:2752
	global_load_dwordx4 v[200:203], v1, s[36:37] offset:2752
	s_waitcnt vmcnt(28)
	v_mfma_f32_16x16x32_bf16 v[32:35], v[212:215], v[204:207], v[32:35]
	v_mfma_f32_16x16x32_bf16 v[52:55], v[212:215], v[208:211], v[52:55]
	v_mfma_f32_16x16x32_bf16 v[36:39], v[234:237], v[204:207], v[36:39]
	v_mfma_f32_16x16x32_bf16 v[56:59], v[234:237], v[208:211], v[56:59]
	v_mfma_f32_16x16x32_bf16 v[40:43], v[238:241], v[204:207], v[40:43]
	v_mfma_f32_16x16x32_bf16 v[60:63], v[238:241], v[208:211], v[60:63]
	v_mfma_f32_16x16x32_bf16 v[44:47], v[242:245], v[204:207], v[44:47]
	v_mfma_f32_16x16x32_bf16 v[64:67], v[242:245], v[208:211], v[64:67]
	v_mfma_f32_16x16x32_bf16 v[48:51], v[246:249], v[204:207], v[48:51]
	v_mfma_f32_16x16x32_bf16 v[68:71], v[246:249], v[208:211], v[68:71]
	global_load_dwordx4 v[204:207], v1, s[8:9] offset:2816
	global_load_dwordx4 v[208:211], v1, s[16:17] offset:2816
	global_load_dwordx4 v[212:215], v1, s[18:19] offset:2816
	global_load_dwordx4 v[234:237], v1, s[28:29] offset:2816
	global_load_dwordx4 v[238:241], v1, s[30:31] offset:2816
	global_load_dwordx4 v[242:245], v1, s[34:35] offset:2816
	global_load_dwordx4 v[246:249], v1, s[36:37] offset:2816
	s_waitcnt vmcnt(28)
	v_mfma_f32_16x16x32_bf16 v[32:35], v[80:83], v[72:75], v[32:35]
	v_mfma_f32_16x16x32_bf16 v[52:55], v[80:83], v[76:79], v[52:55]
	v_mfma_f32_16x16x32_bf16 v[36:39], v[84:87], v[72:75], v[36:39]
	v_mfma_f32_16x16x32_bf16 v[56:59], v[84:87], v[76:79], v[56:59]
	v_mfma_f32_16x16x32_bf16 v[40:43], v[88:91], v[72:75], v[40:43]
	v_mfma_f32_16x16x32_bf16 v[60:63], v[88:91], v[76:79], v[60:63]
	v_mfma_f32_16x16x32_bf16 v[44:47], v[92:95], v[72:75], v[44:47]
	v_mfma_f32_16x16x32_bf16 v[64:67], v[92:95], v[76:79], v[64:67]
	v_mfma_f32_16x16x32_bf16 v[48:51], v[96:99], v[72:75], v[48:51]
	v_mfma_f32_16x16x32_bf16 v[68:71], v[96:99], v[76:79], v[68:71]
	global_load_dwordx4 v[72:75], v1, s[8:9] offset:2880
	global_load_dwordx4 v[76:79], v1, s[16:17] offset:2880
	global_load_dwordx4 v[80:83], v1, s[18:19] offset:2880
	global_load_dwordx4 v[84:87], v1, s[28:29] offset:2880
	global_load_dwordx4 v[88:91], v1, s[30:31] offset:2880
	global_load_dwordx4 v[92:95], v1, s[34:35] offset:2880
	global_load_dwordx4 v[96:99], v1, s[36:37] offset:2880
	s_waitcnt vmcnt(28)
	v_mfma_f32_16x16x32_bf16 v[32:35], v[108:111], v[100:103], v[32:35]
	v_mfma_f32_16x16x32_bf16 v[52:55], v[108:111], v[104:107], v[52:55]
	v_mfma_f32_16x16x32_bf16 v[36:39], v[112:115], v[100:103], v[36:39]
	v_mfma_f32_16x16x32_bf16 v[56:59], v[112:115], v[104:107], v[56:59]
	v_mfma_f32_16x16x32_bf16 v[40:43], v[116:119], v[100:103], v[40:43]
	v_mfma_f32_16x16x32_bf16 v[60:63], v[116:119], v[104:107], v[60:63]
	v_mfma_f32_16x16x32_bf16 v[44:47], v[120:123], v[100:103], v[44:47]
	v_mfma_f32_16x16x32_bf16 v[64:67], v[120:123], v[104:107], v[64:67]
	v_mfma_f32_16x16x32_bf16 v[48:51], v[124:127], v[100:103], v[48:51]
	v_mfma_f32_16x16x32_bf16 v[68:71], v[124:127], v[104:107], v[68:71]
	global_load_dwordx4 v[100:103], v1, s[8:9] offset:2944
	global_load_dwordx4 v[104:107], v1, s[16:17] offset:2944
	global_load_dwordx4 v[108:111], v1, s[18:19] offset:2944
	global_load_dwordx4 v[112:115], v1, s[28:29] offset:2944
	global_load_dwordx4 v[116:119], v1, s[30:31] offset:2944
	global_load_dwordx4 v[120:123], v1, s[34:35] offset:2944
	global_load_dwordx4 v[124:127], v1, s[36:37] offset:2944
	s_waitcnt vmcnt(28)
	v_mfma_f32_16x16x32_bf16 v[32:35], v[136:139], v[128:131], v[32:35]
	v_mfma_f32_16x16x32_bf16 v[52:55], v[136:139], v[132:135], v[52:55]
	v_mfma_f32_16x16x32_bf16 v[36:39], v[140:143], v[128:131], v[36:39]
	v_mfma_f32_16x16x32_bf16 v[56:59], v[140:143], v[132:135], v[56:59]
	v_mfma_f32_16x16x32_bf16 v[40:43], v[144:147], v[128:131], v[40:43]
	v_mfma_f32_16x16x32_bf16 v[60:63], v[144:147], v[132:135], v[60:63]
	v_mfma_f32_16x16x32_bf16 v[44:47], v[148:151], v[128:131], v[44:47]
	v_mfma_f32_16x16x32_bf16 v[64:67], v[148:151], v[132:135], v[64:67]
	v_mfma_f32_16x16x32_bf16 v[48:51], v[152:155], v[128:131], v[48:51]
	v_mfma_f32_16x16x32_bf16 v[68:71], v[152:155], v[132:135], v[68:71]
	global_load_dwordx4 v[128:131], v1, s[8:9] offset:3008
	global_load_dwordx4 v[132:135], v1, s[16:17] offset:3008
	global_load_dwordx4 v[136:139], v1, s[18:19] offset:3008
	global_load_dwordx4 v[140:143], v1, s[28:29] offset:3008
	global_load_dwordx4 v[144:147], v1, s[30:31] offset:3008
	global_load_dwordx4 v[148:151], v1, s[34:35] offset:3008
	global_load_dwordx4 v[152:155], v1, s[36:37] offset:3008
	s_waitcnt vmcnt(28)
	v_mfma_f32_16x16x32_bf16 v[32:35], v[176:179], v[156:159], v[32:35]
	v_mfma_f32_16x16x32_bf16 v[52:55], v[176:179], v[172:175], v[52:55]
	v_mfma_f32_16x16x32_bf16 v[36:39], v[180:183], v[156:159], v[36:39]
	v_mfma_f32_16x16x32_bf16 v[56:59], v[180:183], v[172:175], v[56:59]
	v_mfma_f32_16x16x32_bf16 v[40:43], v[184:187], v[156:159], v[40:43]
	v_mfma_f32_16x16x32_bf16 v[60:63], v[184:187], v[172:175], v[60:63]
	v_mfma_f32_16x16x32_bf16 v[44:47], v[196:199], v[156:159], v[44:47]
	v_mfma_f32_16x16x32_bf16 v[64:67], v[196:199], v[172:175], v[64:67]
	v_mfma_f32_16x16x32_bf16 v[48:51], v[200:203], v[156:159], v[48:51]
	v_mfma_f32_16x16x32_bf16 v[68:71], v[200:203], v[172:175], v[68:71]
	global_load_dwordx4 v[156:159], v1, s[8:9] offset:3072
	global_load_dwordx4 v[172:175], v1, s[16:17] offset:3072
	global_load_dwordx4 v[176:179], v1, s[18:19] offset:3072
	global_load_dwordx4 v[180:183], v1, s[28:29] offset:3072
	global_load_dwordx4 v[184:187], v1, s[30:31] offset:3072
	global_load_dwordx4 v[196:199], v1, s[34:35] offset:3072
	global_load_dwordx4 v[200:203], v1, s[36:37] offset:3072
	s_waitcnt vmcnt(28)
	v_mfma_f32_16x16x32_bf16 v[32:35], v[212:215], v[204:207], v[32:35]
	v_mfma_f32_16x16x32_bf16 v[52:55], v[212:215], v[208:211], v[52:55]
	v_mfma_f32_16x16x32_bf16 v[36:39], v[234:237], v[204:207], v[36:39]
	v_mfma_f32_16x16x32_bf16 v[56:59], v[234:237], v[208:211], v[56:59]
	v_mfma_f32_16x16x32_bf16 v[40:43], v[238:241], v[204:207], v[40:43]
	v_mfma_f32_16x16x32_bf16 v[60:63], v[238:241], v[208:211], v[60:63]
	v_mfma_f32_16x16x32_bf16 v[44:47], v[242:245], v[204:207], v[44:47]
	v_mfma_f32_16x16x32_bf16 v[64:67], v[242:245], v[208:211], v[64:67]
	v_mfma_f32_16x16x32_bf16 v[48:51], v[246:249], v[204:207], v[48:51]
	v_mfma_f32_16x16x32_bf16 v[68:71], v[246:249], v[208:211], v[68:71]
	global_load_dwordx4 v[204:207], v1, s[8:9] offset:3136
	global_load_dwordx4 v[208:211], v1, s[16:17] offset:3136
	global_load_dwordx4 v[212:215], v1, s[18:19] offset:3136
	global_load_dwordx4 v[234:237], v1, s[28:29] offset:3136
	global_load_dwordx4 v[238:241], v1, s[30:31] offset:3136
	global_load_dwordx4 v[242:245], v1, s[34:35] offset:3136
	global_load_dwordx4 v[246:249], v1, s[36:37] offset:3136
	s_waitcnt vmcnt(28)
	v_mfma_f32_16x16x32_bf16 v[32:35], v[80:83], v[72:75], v[32:35]
	v_mfma_f32_16x16x32_bf16 v[52:55], v[80:83], v[76:79], v[52:55]
	v_mfma_f32_16x16x32_bf16 v[36:39], v[84:87], v[72:75], v[36:39]
	v_mfma_f32_16x16x32_bf16 v[56:59], v[84:87], v[76:79], v[56:59]
	v_mfma_f32_16x16x32_bf16 v[40:43], v[88:91], v[72:75], v[40:43]
	v_mfma_f32_16x16x32_bf16 v[60:63], v[88:91], v[76:79], v[60:63]
	v_mfma_f32_16x16x32_bf16 v[44:47], v[92:95], v[72:75], v[44:47]
	v_mfma_f32_16x16x32_bf16 v[64:67], v[92:95], v[76:79], v[64:67]
	v_mfma_f32_16x16x32_bf16 v[48:51], v[96:99], v[72:75], v[48:51]
	v_mfma_f32_16x16x32_bf16 v[68:71], v[96:99], v[76:79], v[68:71]
	global_load_dwordx4 v[72:75], v1, s[8:9] offset:3200
	global_load_dwordx4 v[76:79], v1, s[16:17] offset:3200
	global_load_dwordx4 v[80:83], v1, s[18:19] offset:3200
	global_load_dwordx4 v[84:87], v1, s[28:29] offset:3200
	global_load_dwordx4 v[88:91], v1, s[30:31] offset:3200
	global_load_dwordx4 v[92:95], v1, s[34:35] offset:3200
	global_load_dwordx4 v[96:99], v1, s[36:37] offset:3200
	s_waitcnt vmcnt(28)
	v_mfma_f32_16x16x32_bf16 v[32:35], v[108:111], v[100:103], v[32:35]
	v_mfma_f32_16x16x32_bf16 v[52:55], v[108:111], v[104:107], v[52:55]
	v_mfma_f32_16x16x32_bf16 v[36:39], v[112:115], v[100:103], v[36:39]
	v_mfma_f32_16x16x32_bf16 v[56:59], v[112:115], v[104:107], v[56:59]
	v_mfma_f32_16x16x32_bf16 v[40:43], v[116:119], v[100:103], v[40:43]
	v_mfma_f32_16x16x32_bf16 v[60:63], v[116:119], v[104:107], v[60:63]
	v_mfma_f32_16x16x32_bf16 v[44:47], v[120:123], v[100:103], v[44:47]
	v_mfma_f32_16x16x32_bf16 v[64:67], v[120:123], v[104:107], v[64:67]
	v_mfma_f32_16x16x32_bf16 v[48:51], v[124:127], v[100:103], v[48:51]
	v_mfma_f32_16x16x32_bf16 v[68:71], v[124:127], v[104:107], v[68:71]
	global_load_dwordx4 v[100:103], v1, s[8:9] offset:3264
	global_load_dwordx4 v[104:107], v1, s[16:17] offset:3264
	global_load_dwordx4 v[108:111], v1, s[18:19] offset:3264
	global_load_dwordx4 v[112:115], v1, s[28:29] offset:3264
	global_load_dwordx4 v[116:119], v1, s[30:31] offset:3264
	global_load_dwordx4 v[120:123], v1, s[34:35] offset:3264
	global_load_dwordx4 v[124:127], v1, s[36:37] offset:3264
	s_waitcnt vmcnt(28)
	v_mfma_f32_16x16x32_bf16 v[32:35], v[136:139], v[128:131], v[32:35]
	v_mfma_f32_16x16x32_bf16 v[52:55], v[136:139], v[132:135], v[52:55]
	v_mfma_f32_16x16x32_bf16 v[36:39], v[140:143], v[128:131], v[36:39]
	v_mfma_f32_16x16x32_bf16 v[56:59], v[140:143], v[132:135], v[56:59]
	v_mfma_f32_16x16x32_bf16 v[40:43], v[144:147], v[128:131], v[40:43]
	v_mfma_f32_16x16x32_bf16 v[60:63], v[144:147], v[132:135], v[60:63]
	v_mfma_f32_16x16x32_bf16 v[44:47], v[148:151], v[128:131], v[44:47]
	v_mfma_f32_16x16x32_bf16 v[64:67], v[148:151], v[132:135], v[64:67]
	v_mfma_f32_16x16x32_bf16 v[48:51], v[152:155], v[128:131], v[48:51]
	v_mfma_f32_16x16x32_bf16 v[68:71], v[152:155], v[132:135], v[68:71]
	global_load_dwordx4 v[128:131], v1, s[8:9] offset:3328
	global_load_dwordx4 v[132:135], v1, s[16:17] offset:3328
	global_load_dwordx4 v[136:139], v1, s[18:19] offset:3328
	global_load_dwordx4 v[140:143], v1, s[28:29] offset:3328
	global_load_dwordx4 v[144:147], v1, s[30:31] offset:3328
	global_load_dwordx4 v[148:151], v1, s[34:35] offset:3328
	global_load_dwordx4 v[152:155], v1, s[36:37] offset:3328
	s_waitcnt vmcnt(28)
	v_mfma_f32_16x16x32_bf16 v[32:35], v[176:179], v[156:159], v[32:35]
	v_mfma_f32_16x16x32_bf16 v[52:55], v[176:179], v[172:175], v[52:55]
	v_mfma_f32_16x16x32_bf16 v[36:39], v[180:183], v[156:159], v[36:39]
	v_mfma_f32_16x16x32_bf16 v[56:59], v[180:183], v[172:175], v[56:59]
	v_mfma_f32_16x16x32_bf16 v[40:43], v[184:187], v[156:159], v[40:43]
	v_mfma_f32_16x16x32_bf16 v[60:63], v[184:187], v[172:175], v[60:63]
	v_mfma_f32_16x16x32_bf16 v[44:47], v[196:199], v[156:159], v[44:47]
	v_mfma_f32_16x16x32_bf16 v[64:67], v[196:199], v[172:175], v[64:67]
	v_mfma_f32_16x16x32_bf16 v[48:51], v[200:203], v[156:159], v[48:51]
	v_mfma_f32_16x16x32_bf16 v[68:71], v[200:203], v[172:175], v[68:71]
	global_load_dwordx4 v[156:159], v1, s[8:9] offset:3392
	global_load_dwordx4 v[172:175], v1, s[16:17] offset:3392
	global_load_dwordx4 v[176:179], v1, s[18:19] offset:3392
	global_load_dwordx4 v[180:183], v1, s[28:29] offset:3392
	global_load_dwordx4 v[184:187], v1, s[30:31] offset:3392
	global_load_dwordx4 v[196:199], v1, s[34:35] offset:3392
	global_load_dwordx4 v[200:203], v1, s[36:37] offset:3392
	s_waitcnt vmcnt(28)
	v_mfma_f32_16x16x32_bf16 v[32:35], v[212:215], v[204:207], v[32:35]
	v_mfma_f32_16x16x32_bf16 v[52:55], v[212:215], v[208:211], v[52:55]
	v_mfma_f32_16x16x32_bf16 v[36:39], v[234:237], v[204:207], v[36:39]
	v_mfma_f32_16x16x32_bf16 v[56:59], v[234:237], v[208:211], v[56:59]
	v_mfma_f32_16x16x32_bf16 v[40:43], v[238:241], v[204:207], v[40:43]
	v_mfma_f32_16x16x32_bf16 v[60:63], v[238:241], v[208:211], v[60:63]
	v_mfma_f32_16x16x32_bf16 v[44:47], v[242:245], v[204:207], v[44:47]
	v_mfma_f32_16x16x32_bf16 v[64:67], v[242:245], v[208:211], v[64:67]
	v_mfma_f32_16x16x32_bf16 v[48:51], v[246:249], v[204:207], v[48:51]
	v_mfma_f32_16x16x32_bf16 v[68:71], v[246:249], v[208:211], v[68:71]
	global_load_dwordx4 v[204:207], v1, s[8:9] offset:3456
	global_load_dwordx4 v[208:211], v1, s[16:17] offset:3456
	global_load_dwordx4 v[212:215], v1, s[18:19] offset:3456
	global_load_dwordx4 v[234:237], v1, s[28:29] offset:3456
	global_load_dwordx4 v[238:241], v1, s[30:31] offset:3456
	global_load_dwordx4 v[242:245], v1, s[34:35] offset:3456
	global_load_dwordx4 v[246:249], v1, s[36:37] offset:3456
	s_waitcnt vmcnt(28)
	v_mfma_f32_16x16x32_bf16 v[32:35], v[80:83], v[72:75], v[32:35]
	v_mfma_f32_16x16x32_bf16 v[52:55], v[80:83], v[76:79], v[52:55]
	v_mfma_f32_16x16x32_bf16 v[36:39], v[84:87], v[72:75], v[36:39]
	v_mfma_f32_16x16x32_bf16 v[56:59], v[84:87], v[76:79], v[56:59]
	v_mfma_f32_16x16x32_bf16 v[40:43], v[88:91], v[72:75], v[40:43]
	v_mfma_f32_16x16x32_bf16 v[60:63], v[88:91], v[76:79], v[60:63]
	v_mfma_f32_16x16x32_bf16 v[44:47], v[92:95], v[72:75], v[44:47]
	v_mfma_f32_16x16x32_bf16 v[64:67], v[92:95], v[76:79], v[64:67]
	v_mfma_f32_16x16x32_bf16 v[48:51], v[96:99], v[72:75], v[48:51]
	v_mfma_f32_16x16x32_bf16 v[68:71], v[96:99], v[76:79], v[68:71]
	global_load_dwordx4 v[72:75], v1, s[8:9] offset:3520
	global_load_dwordx4 v[76:79], v1, s[16:17] offset:3520
	global_load_dwordx4 v[80:83], v1, s[18:19] offset:3520
	global_load_dwordx4 v[84:87], v1, s[28:29] offset:3520
	global_load_dwordx4 v[88:91], v1, s[30:31] offset:3520
	global_load_dwordx4 v[92:95], v1, s[34:35] offset:3520
	global_load_dwordx4 v[96:99], v1, s[36:37] offset:3520
	s_waitcnt vmcnt(28)
	v_mfma_f32_16x16x32_bf16 v[32:35], v[108:111], v[100:103], v[32:35]
	v_mfma_f32_16x16x32_bf16 v[52:55], v[108:111], v[104:107], v[52:55]
	v_mfma_f32_16x16x32_bf16 v[36:39], v[112:115], v[100:103], v[36:39]
	v_mfma_f32_16x16x32_bf16 v[56:59], v[112:115], v[104:107], v[56:59]
	v_mfma_f32_16x16x32_bf16 v[40:43], v[116:119], v[100:103], v[40:43]
	v_mfma_f32_16x16x32_bf16 v[60:63], v[116:119], v[104:107], v[60:63]
	v_mfma_f32_16x16x32_bf16 v[44:47], v[120:123], v[100:103], v[44:47]
	v_mfma_f32_16x16x32_bf16 v[64:67], v[120:123], v[104:107], v[64:67]
	v_mfma_f32_16x16x32_bf16 v[48:51], v[124:127], v[100:103], v[48:51]
	v_mfma_f32_16x16x32_bf16 v[68:71], v[124:127], v[104:107], v[68:71]
	global_load_dwordx4 v[100:103], v1, s[8:9] offset:3584
	global_load_dwordx4 v[104:107], v1, s[16:17] offset:3584
	global_load_dwordx4 v[108:111], v1, s[18:19] offset:3584
	global_load_dwordx4 v[112:115], v1, s[28:29] offset:3584
	global_load_dwordx4 v[116:119], v1, s[30:31] offset:3584
	global_load_dwordx4 v[120:123], v1, s[34:35] offset:3584
	global_load_dwordx4 v[124:127], v1, s[36:37] offset:3584
	s_waitcnt vmcnt(28)
	v_mfma_f32_16x16x32_bf16 v[32:35], v[136:139], v[128:131], v[32:35]
	v_mfma_f32_16x16x32_bf16 v[52:55], v[136:139], v[132:135], v[52:55]
	v_mfma_f32_16x16x32_bf16 v[36:39], v[140:143], v[128:131], v[36:39]
	v_mfma_f32_16x16x32_bf16 v[56:59], v[140:143], v[132:135], v[56:59]
	v_mfma_f32_16x16x32_bf16 v[40:43], v[144:147], v[128:131], v[40:43]
	v_mfma_f32_16x16x32_bf16 v[60:63], v[144:147], v[132:135], v[60:63]
	v_mfma_f32_16x16x32_bf16 v[44:47], v[148:151], v[128:131], v[44:47]
	v_mfma_f32_16x16x32_bf16 v[64:67], v[148:151], v[132:135], v[64:67]
	v_mfma_f32_16x16x32_bf16 v[48:51], v[152:155], v[128:131], v[48:51]
	v_mfma_f32_16x16x32_bf16 v[68:71], v[152:155], v[132:135], v[68:71]
	global_load_dwordx4 v[128:131], v1, s[8:9] offset:3648
	global_load_dwordx4 v[132:135], v1, s[16:17] offset:3648
	global_load_dwordx4 v[136:139], v1, s[18:19] offset:3648
	global_load_dwordx4 v[140:143], v1, s[28:29] offset:3648
	global_load_dwordx4 v[144:147], v1, s[30:31] offset:3648
	global_load_dwordx4 v[148:151], v1, s[34:35] offset:3648
	global_load_dwordx4 v[152:155], v1, s[36:37] offset:3648
	s_waitcnt vmcnt(28)
	v_mfma_f32_16x16x32_bf16 v[32:35], v[176:179], v[156:159], v[32:35]
	v_mfma_f32_16x16x32_bf16 v[52:55], v[176:179], v[172:175], v[52:55]
	v_mfma_f32_16x16x32_bf16 v[36:39], v[180:183], v[156:159], v[36:39]
	v_mfma_f32_16x16x32_bf16 v[56:59], v[180:183], v[172:175], v[56:59]
	v_mfma_f32_16x16x32_bf16 v[40:43], v[184:187], v[156:159], v[40:43]
	v_mfma_f32_16x16x32_bf16 v[60:63], v[184:187], v[172:175], v[60:63]
	v_mfma_f32_16x16x32_bf16 v[44:47], v[196:199], v[156:159], v[44:47]
	v_mfma_f32_16x16x32_bf16 v[64:67], v[196:199], v[172:175], v[64:67]
	v_mfma_f32_16x16x32_bf16 v[48:51], v[200:203], v[156:159], v[48:51]
	v_mfma_f32_16x16x32_bf16 v[68:71], v[200:203], v[172:175], v[68:71]
	global_load_dwordx4 v[156:159], v1, s[8:9] offset:3712
	global_load_dwordx4 v[172:175], v1, s[16:17] offset:3712
	global_load_dwordx4 v[176:179], v1, s[18:19] offset:3712
	global_load_dwordx4 v[180:183], v1, s[28:29] offset:3712
	global_load_dwordx4 v[184:187], v1, s[30:31] offset:3712
	global_load_dwordx4 v[196:199], v1, s[34:35] offset:3712
	global_load_dwordx4 v[200:203], v1, s[36:37] offset:3712
	s_waitcnt vmcnt(28)
	v_mfma_f32_16x16x32_bf16 v[32:35], v[212:215], v[204:207], v[32:35]
	v_mfma_f32_16x16x32_bf16 v[52:55], v[212:215], v[208:211], v[52:55]
	v_mfma_f32_16x16x32_bf16 v[36:39], v[234:237], v[204:207], v[36:39]
	v_mfma_f32_16x16x32_bf16 v[56:59], v[234:237], v[208:211], v[56:59]
	v_mfma_f32_16x16x32_bf16 v[40:43], v[238:241], v[204:207], v[40:43]
	v_mfma_f32_16x16x32_bf16 v[60:63], v[238:241], v[208:211], v[60:63]
	v_mfma_f32_16x16x32_bf16 v[44:47], v[242:245], v[204:207], v[44:47]
	v_mfma_f32_16x16x32_bf16 v[64:67], v[242:245], v[208:211], v[64:67]
	v_mfma_f32_16x16x32_bf16 v[48:51], v[246:249], v[204:207], v[48:51]
	v_mfma_f32_16x16x32_bf16 v[68:71], v[246:249], v[208:211], v[68:71]
	global_load_dwordx4 v[204:207], v1, s[8:9] offset:3776
	global_load_dwordx4 v[208:211], v1, s[16:17] offset:3776
	global_load_dwordx4 v[212:215], v1, s[18:19] offset:3776
	global_load_dwordx4 v[234:237], v1, s[28:29] offset:3776
	global_load_dwordx4 v[238:241], v1, s[30:31] offset:3776
	global_load_dwordx4 v[242:245], v1, s[34:35] offset:3776
	global_load_dwordx4 v[246:249], v1, s[36:37] offset:3776
	s_waitcnt vmcnt(28)
	v_mfma_f32_16x16x32_bf16 v[32:35], v[80:83], v[72:75], v[32:35]
	v_mfma_f32_16x16x32_bf16 v[52:55], v[80:83], v[76:79], v[52:55]
	v_mfma_f32_16x16x32_bf16 v[36:39], v[84:87], v[72:75], v[36:39]
	v_mfma_f32_16x16x32_bf16 v[56:59], v[84:87], v[76:79], v[56:59]
	v_mfma_f32_16x16x32_bf16 v[40:43], v[88:91], v[72:75], v[40:43]
	v_mfma_f32_16x16x32_bf16 v[60:63], v[88:91], v[76:79], v[60:63]
	v_mfma_f32_16x16x32_bf16 v[44:47], v[92:95], v[72:75], v[44:47]
	v_mfma_f32_16x16x32_bf16 v[64:67], v[92:95], v[76:79], v[64:67]
	v_mfma_f32_16x16x32_bf16 v[48:51], v[96:99], v[72:75], v[48:51]
	v_mfma_f32_16x16x32_bf16 v[68:71], v[96:99], v[76:79], v[68:71]
	global_load_dwordx4 v[72:75], v1, s[8:9] offset:3840
	global_load_dwordx4 v[76:79], v1, s[16:17] offset:3840
	global_load_dwordx4 v[80:83], v1, s[18:19] offset:3840
	global_load_dwordx4 v[84:87], v1, s[28:29] offset:3840
	global_load_dwordx4 v[88:91], v1, s[30:31] offset:3840
	global_load_dwordx4 v[92:95], v1, s[34:35] offset:3840
	global_load_dwordx4 v[96:99], v1, s[36:37] offset:3840
	s_waitcnt vmcnt(28)
	v_mfma_f32_16x16x32_bf16 v[32:35], v[108:111], v[100:103], v[32:35]
	v_mfma_f32_16x16x32_bf16 v[52:55], v[108:111], v[104:107], v[52:55]
	v_mfma_f32_16x16x32_bf16 v[36:39], v[112:115], v[100:103], v[36:39]
	v_mfma_f32_16x16x32_bf16 v[56:59], v[112:115], v[104:107], v[56:59]
	v_mfma_f32_16x16x32_bf16 v[40:43], v[116:119], v[100:103], v[40:43]
	v_mfma_f32_16x16x32_bf16 v[60:63], v[116:119], v[104:107], v[60:63]
	v_mfma_f32_16x16x32_bf16 v[44:47], v[120:123], v[100:103], v[44:47]
	v_mfma_f32_16x16x32_bf16 v[64:67], v[120:123], v[104:107], v[64:67]
	v_mfma_f32_16x16x32_bf16 v[48:51], v[124:127], v[100:103], v[48:51]
	v_mfma_f32_16x16x32_bf16 v[68:71], v[124:127], v[104:107], v[68:71]
	global_load_dwordx4 v[100:103], v1, s[8:9] offset:3904
	global_load_dwordx4 v[104:107], v1, s[16:17] offset:3904
	global_load_dwordx4 v[108:111], v1, s[18:19] offset:3904
	global_load_dwordx4 v[112:115], v1, s[28:29] offset:3904
	global_load_dwordx4 v[116:119], v1, s[30:31] offset:3904
	global_load_dwordx4 v[120:123], v1, s[34:35] offset:3904
	global_load_dwordx4 v[124:127], v1, s[36:37] offset:3904
	s_waitcnt vmcnt(28)
	v_mfma_f32_16x16x32_bf16 v[32:35], v[136:139], v[128:131], v[32:35]
	v_mfma_f32_16x16x32_bf16 v[52:55], v[136:139], v[132:135], v[52:55]
	v_mfma_f32_16x16x32_bf16 v[36:39], v[140:143], v[128:131], v[36:39]
	v_mfma_f32_16x16x32_bf16 v[56:59], v[140:143], v[132:135], v[56:59]
	v_mfma_f32_16x16x32_bf16 v[40:43], v[144:147], v[128:131], v[40:43]
	v_mfma_f32_16x16x32_bf16 v[60:63], v[144:147], v[132:135], v[60:63]
	v_mfma_f32_16x16x32_bf16 v[44:47], v[148:151], v[128:131], v[44:47]
	v_mfma_f32_16x16x32_bf16 v[64:67], v[148:151], v[132:135], v[64:67]
	v_mfma_f32_16x16x32_bf16 v[48:51], v[152:155], v[128:131], v[48:51]
	v_mfma_f32_16x16x32_bf16 v[68:71], v[152:155], v[132:135], v[68:71]
	global_load_dwordx4 v[128:131], v1, s[8:9] offset:3968
	global_load_dwordx4 v[132:135], v1, s[16:17] offset:3968
	global_load_dwordx4 v[136:139], v1, s[18:19] offset:3968
	global_load_dwordx4 v[140:143], v1, s[28:29] offset:3968
	global_load_dwordx4 v[144:147], v1, s[30:31] offset:3968
	global_load_dwordx4 v[148:151], v1, s[34:35] offset:3968
	global_load_dwordx4 v[152:155], v1, s[36:37] offset:3968
	s_waitcnt vmcnt(28)
	v_mfma_f32_16x16x32_bf16 v[32:35], v[176:179], v[156:159], v[32:35]
	v_mfma_f32_16x16x32_bf16 v[52:55], v[176:179], v[172:175], v[52:55]
	v_mfma_f32_16x16x32_bf16 v[36:39], v[180:183], v[156:159], v[36:39]
	v_mfma_f32_16x16x32_bf16 v[56:59], v[180:183], v[172:175], v[56:59]
	v_mfma_f32_16x16x32_bf16 v[40:43], v[184:187], v[156:159], v[40:43]
	v_mfma_f32_16x16x32_bf16 v[60:63], v[184:187], v[172:175], v[60:63]
	v_mfma_f32_16x16x32_bf16 v[44:47], v[196:199], v[156:159], v[44:47]
	v_mfma_f32_16x16x32_bf16 v[64:67], v[196:199], v[172:175], v[64:67]
	v_mfma_f32_16x16x32_bf16 v[48:51], v[200:203], v[156:159], v[48:51]
	v_mfma_f32_16x16x32_bf16 v[68:71], v[200:203], v[172:175], v[68:71]
	global_load_dwordx4 v[156:159], v1, s[8:9] offset:4032
	global_load_dwordx4 v[172:175], v1, s[16:17] offset:4032
	global_load_dwordx4 v[176:179], v1, s[18:19] offset:4032
	global_load_dwordx4 v[180:183], v1, s[28:29] offset:4032
	global_load_dwordx4 v[184:187], v1, s[30:31] offset:4032
	global_load_dwordx4 v[196:199], v1, s[34:35] offset:4032
	global_load_dwordx4 v[200:203], v1, s[36:37] offset:4032
	s_waitcnt vmcnt(28)
	v_mfma_f32_16x16x32_bf16 v[32:35], v[212:215], v[204:207], v[32:35]
	v_mfma_f32_16x16x32_bf16 v[52:55], v[212:215], v[208:211], v[52:55]
	v_mfma_f32_16x16x32_bf16 v[36:39], v[234:237], v[204:207], v[36:39]
	v_mfma_f32_16x16x32_bf16 v[56:59], v[234:237], v[208:211], v[56:59]
	v_mfma_f32_16x16x32_bf16 v[40:43], v[238:241], v[204:207], v[40:43]
	v_mfma_f32_16x16x32_bf16 v[60:63], v[238:241], v[208:211], v[60:63]
	v_mfma_f32_16x16x32_bf16 v[44:47], v[242:245], v[204:207], v[44:47]
	v_mfma_f32_16x16x32_bf16 v[64:67], v[242:245], v[208:211], v[64:67]
	v_mfma_f32_16x16x32_bf16 v[48:51], v[246:249], v[204:207], v[48:51]
	v_mfma_f32_16x16x32_bf16 v[68:71], v[246:249], v[208:211], v[68:71]
	s_waitcnt vmcnt(21)
	v_mfma_f32_16x16x32_bf16 v[32:35], v[80:83], v[72:75], v[32:35]
	v_mfma_f32_16x16x32_bf16 v[52:55], v[80:83], v[76:79], v[52:55]
	v_mfma_f32_16x16x32_bf16 v[36:39], v[84:87], v[72:75], v[36:39]
	v_mfma_f32_16x16x32_bf16 v[56:59], v[84:87], v[76:79], v[56:59]
	v_mfma_f32_16x16x32_bf16 v[40:43], v[88:91], v[72:75], v[40:43]
	v_mfma_f32_16x16x32_bf16 v[60:63], v[88:91], v[76:79], v[60:63]
	v_mfma_f32_16x16x32_bf16 v[44:47], v[92:95], v[72:75], v[44:47]
	v_mfma_f32_16x16x32_bf16 v[64:67], v[92:95], v[76:79], v[64:67]
	v_mfma_f32_16x16x32_bf16 v[48:51], v[96:99], v[72:75], v[48:51]
	v_mfma_f32_16x16x32_bf16 v[68:71], v[96:99], v[76:79], v[68:71]
	s_waitcnt vmcnt(14)
	v_mfma_f32_16x16x32_bf16 v[32:35], v[108:111], v[100:103], v[32:35]
	v_mfma_f32_16x16x32_bf16 v[52:55], v[108:111], v[104:107], v[52:55]
	v_mfma_f32_16x16x32_bf16 v[36:39], v[112:115], v[100:103], v[36:39]
	v_mfma_f32_16x16x32_bf16 v[56:59], v[112:115], v[104:107], v[56:59]
	v_mfma_f32_16x16x32_bf16 v[40:43], v[116:119], v[100:103], v[40:43]
	v_mfma_f32_16x16x32_bf16 v[60:63], v[116:119], v[104:107], v[60:63]
	v_mfma_f32_16x16x32_bf16 v[44:47], v[120:123], v[100:103], v[44:47]
	v_mfma_f32_16x16x32_bf16 v[64:67], v[120:123], v[104:107], v[64:67]
	v_mfma_f32_16x16x32_bf16 v[48:51], v[124:127], v[100:103], v[48:51]
	v_mfma_f32_16x16x32_bf16 v[68:71], v[124:127], v[104:107], v[68:71]
	s_waitcnt vmcnt(7)
	v_mfma_f32_16x16x32_bf16 v[32:35], v[136:139], v[128:131], v[32:35]
	v_mfma_f32_16x16x32_bf16 v[52:55], v[136:139], v[132:135], v[52:55]
	v_mfma_f32_16x16x32_bf16 v[36:39], v[140:143], v[128:131], v[36:39]
	v_mfma_f32_16x16x32_bf16 v[56:59], v[140:143], v[132:135], v[56:59]
	v_mfma_f32_16x16x32_bf16 v[40:43], v[144:147], v[128:131], v[40:43]
	v_mfma_f32_16x16x32_bf16 v[60:63], v[144:147], v[132:135], v[60:63]
	v_mfma_f32_16x16x32_bf16 v[44:47], v[148:151], v[128:131], v[44:47]
	v_mfma_f32_16x16x32_bf16 v[64:67], v[148:151], v[132:135], v[64:67]
	v_mfma_f32_16x16x32_bf16 v[48:51], v[152:155], v[128:131], v[48:51]
	v_mfma_f32_16x16x32_bf16 v[68:71], v[152:155], v[132:135], v[68:71]
	s_waitcnt vmcnt(0)
	v_mfma_f32_16x16x32_bf16 v[32:35], v[176:179], v[156:159], v[32:35]
	v_mfma_f32_16x16x32_bf16 v[52:55], v[176:179], v[172:175], v[52:55]
	v_mfma_f32_16x16x32_bf16 v[36:39], v[180:183], v[156:159], v[36:39]
	v_mfma_f32_16x16x32_bf16 v[56:59], v[180:183], v[172:175], v[56:59]
	v_mfma_f32_16x16x32_bf16 v[40:43], v[184:187], v[156:159], v[40:43]
	v_mfma_f32_16x16x32_bf16 v[60:63], v[184:187], v[172:175], v[60:63]
	v_mfma_f32_16x16x32_bf16 v[44:47], v[196:199], v[156:159], v[44:47]
	v_mfma_f32_16x16x32_bf16 v[64:67], v[196:199], v[172:175], v[64:67]
	v_mfma_f32_16x16x32_bf16 v[48:51], v[200:203], v[156:159], v[48:51]
	v_mfma_f32_16x16x32_bf16 v[68:71], v[200:203], v[172:175], v[68:71]
	global_load_dwordx4 v[72:75], v3, s[38:39]
	global_load_dwordx4 v[76:79], v3, s[38:39] offset:64
	global_load_dwordx4 v[80:83], v3, s[38:39] offset:128
	global_load_dwordx4 v[84:87], v3, s[38:39] offset:192
	global_load_dwordx4 v[88:91], v3, s[38:39] offset:256
	s_nop 7
	s_waitcnt vmcnt(0)
	v_add_f32_e32 v32, v32, v72
	v_add_f32_e32 v33, v33, v73
	v_add_f32_e32 v34, v34, v74
	v_add_f32_e32 v35, v35, v75
	v_add_f32_e32 v36, v36, v76
	v_add_f32_e32 v37, v37, v77
	v_add_f32_e32 v38, v38, v78
	v_add_f32_e32 v39, v39, v79
	v_add_f32_e32 v40, v40, v80
	v_add_f32_e32 v41, v41, v81
	v_add_f32_e32 v42, v42, v82
	v_add_f32_e32 v43, v43, v83
	v_add_f32_e32 v44, v44, v84
	v_add_f32_e32 v45, v45, v85
	v_add_f32_e32 v46, v46, v86
	v_add_f32_e32 v47, v47, v87
	v_add_f32_e32 v48, v48, v88
	v_add_f32_e32 v49, v49, v89
	v_add_f32_e32 v50, v50, v90
	v_add_f32_e32 v51, v51, v91
	v_add_f32_e32 v52, v52, v72
	v_add_f32_e32 v53, v53, v73
	v_add_f32_e32 v54, v54, v74
	v_add_f32_e32 v55, v55, v75
	v_add_f32_e32 v56, v56, v76
	v_add_f32_e32 v57, v57, v77
	v_add_f32_e32 v58, v58, v78
	v_add_f32_e32 v59, v59, v79
	v_add_f32_e32 v60, v60, v80
	v_add_f32_e32 v61, v61, v81
	v_add_f32_e32 v62, v62, v82
	v_add_f32_e32 v63, v63, v83
	v_add_f32_e32 v64, v64, v84
	v_add_f32_e32 v65, v65, v85
	v_add_f32_e32 v66, v66, v86
	v_add_f32_e32 v67, v67, v87
	v_add_f32_e32 v68, v68, v88
	v_add_f32_e32 v69, v69, v89
	v_add_f32_e32 v70, v70, v90
	v_add_f32_e32 v71, v71, v91
	s_nop 1
	global_store_dwordx4 v2, v[32:35], s[40:41]
	global_store_dwordx4 v2, v[36:39], s[40:41] offset:64
	global_store_dwordx4 v2, v[40:43], s[40:41] offset:128
	global_store_dwordx4 v2, v[44:47], s[40:41] offset:192
	global_store_dwordx4 v2, v[48:51], s[40:41] offset:256
	global_store_dwordx4 v2, v[52:55], s[46:47]
	global_store_dwordx4 v2, v[56:59], s[46:47] offset:64
	global_store_dwordx4 v2, v[60:63], s[46:47] offset:128
	global_store_dwordx4 v2, v[64:67], s[46:47] offset:192
	global_store_dwordx4 v2, v[68:71], s[46:47] offset:256
	s_nop 1
	s_add_i32 s5, s5, s48
	s_branch .Lmisc_unit
